# fused epilogue: sibling exchange via self-validating 8-byte {row partial, tag} granules polled directly (no counter, two barriers fewer)
# speedup vs baseline: 1.0176x; 1.0176x over previous
;     __device__ __forceinline__ void operator()(const Acc& acc, const Unit& u, int wr, int wc, int fr, int fq) const {
;     ...
;             for (int m = 0; m < 4; ++m) { const int row = u.pm * 256 + ai * 128 + wr * 64 + m * 16 + fr;
;                 const float* base = xp ? (row < MP ? xp + (size_t)row * D : xs + (size_t)(row - MP) * D) : X + (size_t)row * D;
;                 const float* gp = gate + (size_t)mod_row(row) * 6144;
; #pragma unroll
;                 for (int bj = 0; bj < 2; ++bj)
; #pragma unroll
;                     for (int n = 0; n < 2; ++n) { const int col = u.pn * 256 + bj * 128 + wc * 32 + n * 16 + fq * 4;
;                         const f32x4 ga = *(const f32x4*)(gp + col) * acc[ai][bj][m][n];
;                         if (u.split) { *(f32x4*)(part + ((size_t)(u.k0 >> 8) * MS + (row - MP)) * D + col) = ga;
;                         } else *(f32x4*)(X + (size_t)row * D + col) = *(const f32x4*)(base + col) + ga; } }
.LBB0_1439:
	s_lshl_b32 s2, s4, 8
	s_add_i32 s2, s2, s55
	s_lshl_b32 s3, s36, 8
	s_add_i32 s3, s3, s56
	v_add_u32_e32 v207, s2, v155
	v_lshl_add_u32 v159, v156, 2, s3
	v_mov_b32_e32 v197, 0
	s_mov_b32 s70, 0x10000
	s_mov_b32 s71, 0
	s_mov_b32 s98, 0x50000
	s_mov_b32 s99, 0
	s_cmp_lg_u32 s63, 0
	s_cbranch_scc1 .Lepi_out_split
	s_mov_b32 s66, 0x10000
	s_mov_b32 s67, 0
	s_mov_b32 s68, 0x50000
	s_mov_b32 s69, 0
	v_lshlrev_b32_e32 v140, 11, v207
	v_lshl_add_u32 v140, v159, 1, v140
	v_mov_b32_e32 v141, 0
	s_add_u32 s70, s16, 0x4200000
	s_addc_u32 s71, s17, 0
	v_lshl_add_u64 v[128:129], v[140:141], 0, s[70:71]
	v_lshlrev_b32_e32 v196, 12, v207
	v_lshl_add_u32 v196, v159, 2, v196
	v_add_u32_e32 v142, s55, v155
	v_lshrrev_b32_e32 v207, 12, v207
	v_lshlrev_b32_e32 v159, 2, v159
	v_mad_u32_u24 v130, v207, s80, v159
	v_mov_b32_e32 v131, 0
	v_lshl_add_u64 v[130:131], v[130:131], 0, s[18:19]
	global_load_dwordx4 v[240:243], v[130:131], off
	global_load_dwordx4 v[244:247], v[130:131], off offset:64
	global_load_dwordx4 v[248:251], v[130:131], off offset:512
	global_load_dwordx4 v[184:187], v[130:131], off offset:576
	s_cmp_lg_u64 s[22:23], 0
	s_cselect_b32 s2, s8, s16
	s_cselect_b32 s3, s9, s17
	v_lshl_add_u64 v[144:145], v[196:197], 0, s[2:3]
	v_lshl_add_u64 v[146:147], v[196:197], 0, s[16:17]
	v_mov_b32_e32 v188, 0
	v_mov_b32_e32 v189, 0
	v_mov_b32_e32 v190, 0
	v_mov_b32_e32 v191, 0
	v_mov_b32_e32 v192, 0
	v_mov_b32_e32 v193, 0
	v_mov_b32_e32 v194, 0
	v_mov_b32_e32 v195, 0
	global_load_dwordx4 v[208:211], v[144:145], off
	global_load_dwordx4 v[212:215], v[144:145], off offset:64
	global_load_dwordx4 v[216:219], v[144:145], off offset:512
	global_load_dwordx4 v[220:223], v[144:145], off offset:576
	v_lshl_add_u64 v[144:145], v[144:145], 0, s[66:67]
	global_load_dwordx4 v[224:227], v[144:145], off
	global_load_dwordx4 v[228:231], v[144:145], off offset:64
	global_load_dwordx4 v[232:235], v[144:145], off offset:512
	global_load_dwordx4 v[236:239], v[144:145], off offset:576
	v_lshl_add_u64 v[144:145], v[144:145], 0, s[66:67]
	s_waitcnt vmcnt(4)
	v_pk_mul_f32 v[126:127], v[126:127], v[242:243]
	v_pk_mul_f32 v[124:125], v[124:125], v[240:241]
	v_pk_add_f32 v[126:127], v[126:127], v[210:211]
	v_pk_add_f32 v[124:125], v[124:125], v[208:209]
	v_pk_mul_f32 v[122:123], v[122:123], v[246:247]
	v_pk_mul_f32 v[120:121], v[120:121], v[244:245]
	v_pk_add_f32 v[122:123], v[122:123], v[214:215]
	v_pk_add_f32 v[120:121], v[120:121], v[212:213]
	v_pk_mul_f32 v[118:119], v[118:119], v[250:251]
	v_pk_mul_f32 v[116:117], v[116:117], v[248:249]
	v_pk_add_f32 v[118:119], v[118:119], v[218:219]
	v_pk_add_f32 v[116:117], v[116:117], v[216:217]
	v_pk_mul_f32 v[114:115], v[114:115], v[186:187]
	v_pk_mul_f32 v[112:113], v[112:113], v[184:185]
	v_pk_add_f32 v[114:115], v[114:115], v[222:223]
	v_pk_add_f32 v[112:113], v[112:113], v[220:221]
	v_pk_mul_f32 v[140:141], v[124:125], v[124:125]
	v_pk_fma_f32 v[140:141], v[126:127], v[126:127], v[140:141]
	v_add_f32_e32 v188, v188, v140
	v_add_f32_e32 v188, v188, v141
	v_pk_mul_f32 v[140:141], v[120:121], v[120:121]
	v_pk_fma_f32 v[140:141], v[122:123], v[122:123], v[140:141]
	v_add_f32_e32 v188, v188, v140
	v_add_f32_e32 v188, v188, v141
	v_pk_mul_f32 v[140:141], v[116:117], v[116:117]
	v_pk_fma_f32 v[140:141], v[118:119], v[118:119], v[140:141]
	v_add_f32_e32 v188, v188, v140
	v_add_f32_e32 v188, v188, v141
	v_pk_mul_f32 v[140:141], v[112:113], v[112:113]
	v_pk_fma_f32 v[140:141], v[114:115], v[114:115], v[140:141]
	v_add_f32_e32 v188, v188, v140
	v_add_f32_e32 v188, v188, v141
	global_load_dwordx4 v[208:211], v[144:145], off
	global_load_dwordx4 v[212:215], v[144:145], off offset:64
	global_load_dwordx4 v[216:219], v[144:145], off offset:512
	global_load_dwordx4 v[220:223], v[144:145], off offset:576
	v_lshl_add_u64 v[144:145], v[144:145], 0, s[66:67]
	s_waitcnt vmcnt(4)
	v_pk_mul_f32 v[110:111], v[110:111], v[242:243]
	v_pk_mul_f32 v[108:109], v[108:109], v[240:241]
	v_pk_add_f32 v[110:111], v[110:111], v[226:227]
	v_pk_add_f32 v[108:109], v[108:109], v[224:225]
	v_pk_mul_f32 v[106:107], v[106:107], v[246:247]
	v_pk_mul_f32 v[104:105], v[104:105], v[244:245]
	v_pk_add_f32 v[106:107], v[106:107], v[230:231]
	v_pk_add_f32 v[104:105], v[104:105], v[228:229]
	v_pk_mul_f32 v[102:103], v[102:103], v[250:251]
	v_pk_mul_f32 v[100:101], v[100:101], v[248:249]
	v_pk_add_f32 v[102:103], v[102:103], v[234:235]
	v_pk_add_f32 v[100:101], v[100:101], v[232:233]
	v_pk_mul_f32 v[98:99], v[98:99], v[186:187]
	v_pk_mul_f32 v[96:97], v[96:97], v[184:185]
	v_pk_add_f32 v[98:99], v[98:99], v[238:239]
	v_pk_add_f32 v[96:97], v[96:97], v[236:237]
	v_pk_mul_f32 v[140:141], v[108:109], v[108:109]
	v_pk_fma_f32 v[140:141], v[110:111], v[110:111], v[140:141]
	v_add_f32_e32 v189, v189, v140
	v_add_f32_e32 v189, v189, v141
	v_pk_mul_f32 v[140:141], v[104:105], v[104:105]
	v_pk_fma_f32 v[140:141], v[106:107], v[106:107], v[140:141]
	v_add_f32_e32 v189, v189, v140
	v_add_f32_e32 v189, v189, v141
	v_pk_mul_f32 v[140:141], v[100:101], v[100:101]
	v_pk_fma_f32 v[140:141], v[102:103], v[102:103], v[140:141]
	v_add_f32_e32 v189, v189, v140
	v_add_f32_e32 v189, v189, v141
	v_pk_mul_f32 v[140:141], v[96:97], v[96:97]
	v_pk_fma_f32 v[140:141], v[98:99], v[98:99], v[140:141]
	v_add_f32_e32 v189, v189, v140
	v_add_f32_e32 v189, v189, v141
	global_load_dwordx4 v[224:227], v[144:145], off
	global_load_dwordx4 v[228:231], v[144:145], off offset:64
	global_load_dwordx4 v[232:235], v[144:145], off offset:512
	global_load_dwordx4 v[236:239], v[144:145], off offset:576
	v_lshl_add_u64 v[144:145], v[144:145], 0, s[68:69]
	s_waitcnt vmcnt(4)
;     __device__ __forceinline__ void operator()(const Acc& acc, const Unit& u, int wr, int wc, int fr, int fq) const {
;     ...
;             for (int m = 0; m < 4; ++m) { const int row = u.pm * 256 + ai * 128 + wr * 64 + m * 16 + fr;
;                 const float* base = xp ? (row < MP ? xp + (size_t)row * D : xs + (size_t)(row - MP) * D) : X + (size_t)row * D;
;                 const float* gp = gate + (size_t)mod_row(row) * 6144;
; #pragma unroll
;                 for (int bj = 0; bj < 2; ++bj)
; #pragma unroll
;                     for (int n = 0; n < 2; ++n) { const int col = u.pn * 256 + bj * 128 + wc * 32 + n * 16 + fq * 4;
;                         const f32x4 ga = *(const f32x4*)(gp + col) * acc[ai][bj][m][n];
;                         if (u.split) { *(f32x4*)(part + ((size_t)(u.k0 >> 8) * MS + (row - MP)) * D + col) = ga;
;                         } else *(f32x4*)(X + (size_t)row * D + col) = *(const f32x4*)(base + col) + ga; } }
	v_pk_mul_f32 v[94:95], v[94:95], v[242:243]
	v_pk_mul_f32 v[92:93], v[92:93], v[240:241]
	v_pk_add_f32 v[94:95], v[94:95], v[210:211]
	v_pk_add_f32 v[92:93], v[92:93], v[208:209]
	v_pk_mul_f32 v[90:91], v[90:91], v[246:247]
	v_pk_mul_f32 v[88:89], v[88:89], v[244:245]
	v_pk_add_f32 v[90:91], v[90:91], v[214:215]
	v_pk_add_f32 v[88:89], v[88:89], v[212:213]
	v_pk_mul_f32 v[86:87], v[86:87], v[250:251]
	v_pk_mul_f32 v[84:85], v[84:85], v[248:249]
	v_pk_add_f32 v[86:87], v[86:87], v[218:219]
	v_pk_add_f32 v[84:85], v[84:85], v[216:217]
	v_pk_mul_f32 v[82:83], v[82:83], v[186:187]
	v_pk_mul_f32 v[80:81], v[80:81], v[184:185]
	v_pk_add_f32 v[82:83], v[82:83], v[222:223]
	v_pk_add_f32 v[80:81], v[80:81], v[220:221]
	v_pk_mul_f32 v[140:141], v[92:93], v[92:93]
	v_pk_fma_f32 v[140:141], v[94:95], v[94:95], v[140:141]
	v_add_f32_e32 v190, v190, v140
	v_add_f32_e32 v190, v190, v141
	v_pk_mul_f32 v[140:141], v[88:89], v[88:89]
	v_pk_fma_f32 v[140:141], v[90:91], v[90:91], v[140:141]
	v_add_f32_e32 v190, v190, v140
	v_add_f32_e32 v190, v190, v141
	v_pk_mul_f32 v[140:141], v[84:85], v[84:85]
	v_pk_fma_f32 v[140:141], v[86:87], v[86:87], v[140:141]
	v_add_f32_e32 v190, v190, v140
	v_add_f32_e32 v190, v190, v141
	v_pk_mul_f32 v[140:141], v[80:81], v[80:81]
	v_pk_fma_f32 v[140:141], v[82:83], v[82:83], v[140:141]
	v_add_f32_e32 v190, v190, v140
	v_add_f32_e32 v190, v190, v141
	global_load_dwordx4 v[208:211], v[144:145], off
	global_load_dwordx4 v[212:215], v[144:145], off offset:64
	global_load_dwordx4 v[216:219], v[144:145], off offset:512
	global_load_dwordx4 v[220:223], v[144:145], off offset:576
	v_lshl_add_u64 v[144:145], v[144:145], 0, s[66:67]
	s_waitcnt vmcnt(4)
	v_pk_mul_f32 v[78:79], v[78:79], v[242:243]
	v_pk_mul_f32 v[76:77], v[76:77], v[240:241]
	v_pk_add_f32 v[78:79], v[78:79], v[226:227]
	v_pk_add_f32 v[76:77], v[76:77], v[224:225]
	v_pk_mul_f32 v[74:75], v[74:75], v[246:247]
	v_pk_mul_f32 v[72:73], v[72:73], v[244:245]
	v_pk_add_f32 v[74:75], v[74:75], v[230:231]
	v_pk_add_f32 v[72:73], v[72:73], v[228:229]
	v_pk_mul_f32 v[70:71], v[70:71], v[250:251]
	v_pk_mul_f32 v[68:69], v[68:69], v[248:249]
	v_pk_add_f32 v[70:71], v[70:71], v[234:235]
	v_pk_add_f32 v[68:69], v[68:69], v[232:233]
	v_pk_mul_f32 v[66:67], v[66:67], v[186:187]
	v_pk_mul_f32 v[64:65], v[64:65], v[184:185]
	v_pk_add_f32 v[66:67], v[66:67], v[238:239]
	v_pk_add_f32 v[64:65], v[64:65], v[236:237]
	v_pk_mul_f32 v[140:141], v[76:77], v[76:77]
	v_pk_fma_f32 v[140:141], v[78:79], v[78:79], v[140:141]
	v_add_f32_e32 v191, v191, v140
	v_add_f32_e32 v191, v191, v141
	v_pk_mul_f32 v[140:141], v[72:73], v[72:73]
	v_pk_fma_f32 v[140:141], v[74:75], v[74:75], v[140:141]
	v_add_f32_e32 v191, v191, v140
	v_add_f32_e32 v191, v191, v141
	v_pk_mul_f32 v[140:141], v[68:69], v[68:69]
	v_pk_fma_f32 v[140:141], v[70:71], v[70:71], v[140:141]
	v_add_f32_e32 v191, v191, v140
	v_add_f32_e32 v191, v191, v141
	v_pk_mul_f32 v[140:141], v[64:65], v[64:65]
	v_pk_fma_f32 v[140:141], v[66:67], v[66:67], v[140:141]
	v_add_f32_e32 v191, v191, v140
	v_add_f32_e32 v191, v191, v141
	global_load_dwordx4 v[224:227], v[144:145], off
	global_load_dwordx4 v[228:231], v[144:145], off offset:64
	global_load_dwordx4 v[232:235], v[144:145], off offset:512
	global_load_dwordx4 v[236:239], v[144:145], off offset:576
	v_lshl_add_u64 v[144:145], v[144:145], 0, s[66:67]
	s_waitcnt vmcnt(4)
	v_pk_mul_f32 v[62:63], v[62:63], v[242:243]
	v_pk_mul_f32 v[60:61], v[60:61], v[240:241]
	v_pk_add_f32 v[62:63], v[62:63], v[210:211]
	v_pk_add_f32 v[60:61], v[60:61], v[208:209]
	v_pk_mul_f32 v[58:59], v[58:59], v[246:247]
	v_pk_mul_f32 v[56:57], v[56:57], v[244:245]
	v_pk_add_f32 v[58:59], v[58:59], v[214:215]
	v_pk_add_f32 v[56:57], v[56:57], v[212:213]
	v_pk_mul_f32 v[54:55], v[54:55], v[250:251]
	v_pk_mul_f32 v[52:53], v[52:53], v[248:249]
	v_pk_add_f32 v[54:55], v[54:55], v[218:219]
	v_pk_add_f32 v[52:53], v[52:53], v[216:217]
	v_pk_mul_f32 v[50:51], v[50:51], v[186:187]
	v_pk_mul_f32 v[48:49], v[48:49], v[184:185]
	v_pk_add_f32 v[50:51], v[50:51], v[222:223]
	v_pk_add_f32 v[48:49], v[48:49], v[220:221]
	v_pk_mul_f32 v[140:141], v[60:61], v[60:61]
	v_pk_fma_f32 v[140:141], v[62:63], v[62:63], v[140:141]
	v_add_f32_e32 v192, v192, v140
	v_add_f32_e32 v192, v192, v141
	v_pk_mul_f32 v[140:141], v[56:57], v[56:57]
	v_pk_fma_f32 v[140:141], v[58:59], v[58:59], v[140:141]
	v_add_f32_e32 v192, v192, v140
	v_add_f32_e32 v192, v192, v141
	v_pk_mul_f32 v[140:141], v[52:53], v[52:53]
	v_pk_fma_f32 v[140:141], v[54:55], v[54:55], v[140:141]
	v_add_f32_e32 v192, v192, v140
	v_add_f32_e32 v192, v192, v141
	v_pk_mul_f32 v[140:141], v[48:49], v[48:49]
	v_pk_fma_f32 v[140:141], v[50:51], v[50:51], v[140:141]
	v_add_f32_e32 v192, v192, v140
	v_add_f32_e32 v192, v192, v141
	global_load_dwordx4 v[208:211], v[144:145], off
	global_load_dwordx4 v[212:215], v[144:145], off offset:64
	global_load_dwordx4 v[216:219], v[144:145], off offset:512
	global_load_dwordx4 v[220:223], v[144:145], off offset:576
	v_lshl_add_u64 v[144:145], v[144:145], 0, s[66:67]
	s_waitcnt vmcnt(4)
;     __device__ __forceinline__ void operator()(const Acc& acc, const Unit& u, int wr, int wc, int fr, int fq) const {
; #pragma unroll
;         for (int ai = 0; ai < 2; ++ai)
; #pragma unroll
;             for (int m = 0; m < 4; ++m) { const int row = u.pm * 256 + ai * 128 + wr * 64 + m * 16 + fr;
;                 const float* base = xp ? (row < MP ? xp + (size_t)row * D : xs + (size_t)(row - MP) * D) : X + (size_t)row * D;
;                 const float* gp = gate + (size_t)mod_row(row) * 6144;
; #pragma unroll
;                 for (int bj = 0; bj < 2; ++bj)
; #pragma unroll
;                     for (int n = 0; n < 2; ++n) { const int col = u.pn * 256 + bj * 128 + wc * 32 + n * 16 + fq * 4;
;                         const f32x4 ga = *(const f32x4*)(gp + col) * acc[ai][bj][m][n];
;                         if (u.split) { *(f32x4*)(part + ((size_t)(u.k0 >> 8) * MS + (row - MP)) * D + col) = ga;
;                         } else *(f32x4*)(X + (size_t)row * D + col) = *(const f32x4*)(base + col) + ga; } }
; template <bool FINAL>
; __device__ __forceinline__ void norm_rows(const float* xp, const float* xs, const float* X, const float* g, const float* sh, const float* sc, bf16_t* XN, float* out, int gw, int NGW, int lane, const float* part, int nsplit) {
;     ...
;         for (int j = 0; j < 4; ++j) s += (v[j][0] * v[j][0] + v[j][1] * v[j][1]) + (v[j][2] * v[j][2] + v[j][3] * v[j][3]);
;         const float rstd = 1.0f / sqrtf(wave_sum(s) * (1.0f / D) + EPS);
	v_pk_mul_f32 v[46:47], v[46:47], v[242:243]
	v_pk_mul_f32 v[44:45], v[44:45], v[240:241]
	v_pk_add_f32 v[46:47], v[46:47], v[226:227]
	v_pk_add_f32 v[44:45], v[44:45], v[224:225]
	v_pk_mul_f32 v[42:43], v[42:43], v[246:247]
	v_pk_mul_f32 v[40:41], v[40:41], v[244:245]
	v_pk_add_f32 v[42:43], v[42:43], v[230:231]
	v_pk_add_f32 v[40:41], v[40:41], v[228:229]
	v_pk_mul_f32 v[38:39], v[38:39], v[250:251]
	v_pk_mul_f32 v[36:37], v[36:37], v[248:249]
	v_pk_add_f32 v[38:39], v[38:39], v[234:235]
	v_pk_add_f32 v[36:37], v[36:37], v[232:233]
	v_pk_mul_f32 v[34:35], v[34:35], v[186:187]
	v_pk_mul_f32 v[32:33], v[32:33], v[184:185]
	v_pk_add_f32 v[34:35], v[34:35], v[238:239]
	v_pk_add_f32 v[32:33], v[32:33], v[236:237]
	v_pk_mul_f32 v[140:141], v[44:45], v[44:45]
	v_pk_fma_f32 v[140:141], v[46:47], v[46:47], v[140:141]
	v_add_f32_e32 v193, v193, v140
	v_add_f32_e32 v193, v193, v141
	v_pk_mul_f32 v[140:141], v[40:41], v[40:41]
	v_pk_fma_f32 v[140:141], v[42:43], v[42:43], v[140:141]
	v_add_f32_e32 v193, v193, v140
	v_add_f32_e32 v193, v193, v141
	v_pk_mul_f32 v[140:141], v[36:37], v[36:37]
	v_pk_fma_f32 v[140:141], v[38:39], v[38:39], v[140:141]
	v_add_f32_e32 v193, v193, v140
	v_add_f32_e32 v193, v193, v141
	v_pk_mul_f32 v[140:141], v[32:33], v[32:33]
	v_pk_fma_f32 v[140:141], v[34:35], v[34:35], v[140:141]
	v_add_f32_e32 v193, v193, v140
	v_add_f32_e32 v193, v193, v141
	global_load_dwordx4 v[224:227], v[144:145], off
	global_load_dwordx4 v[228:231], v[144:145], off offset:64
	global_load_dwordx4 v[232:235], v[144:145], off offset:512
	global_load_dwordx4 v[236:239], v[144:145], off offset:576
	s_waitcnt vmcnt(4)
	v_pk_mul_f32 v[30:31], v[30:31], v[242:243]
	v_pk_mul_f32 v[28:29], v[28:29], v[240:241]
	v_pk_add_f32 v[30:31], v[30:31], v[210:211]
	v_pk_add_f32 v[28:29], v[28:29], v[208:209]
	v_pk_mul_f32 v[26:27], v[26:27], v[246:247]
	v_pk_mul_f32 v[24:25], v[24:25], v[244:245]
	v_pk_add_f32 v[26:27], v[26:27], v[214:215]
	v_pk_add_f32 v[24:25], v[24:25], v[212:213]
	v_pk_mul_f32 v[22:23], v[22:23], v[250:251]
	v_pk_mul_f32 v[20:21], v[20:21], v[248:249]
	v_pk_add_f32 v[22:23], v[22:23], v[218:219]
	v_pk_add_f32 v[20:21], v[20:21], v[216:217]
	v_pk_mul_f32 v[18:19], v[18:19], v[186:187]
	v_pk_mul_f32 v[16:17], v[16:17], v[184:185]
	v_pk_add_f32 v[18:19], v[18:19], v[222:223]
	v_pk_add_f32 v[16:17], v[16:17], v[220:221]
	v_pk_mul_f32 v[140:141], v[28:29], v[28:29]
	v_pk_fma_f32 v[140:141], v[30:31], v[30:31], v[140:141]
	v_add_f32_e32 v194, v194, v140
	v_add_f32_e32 v194, v194, v141
	v_pk_mul_f32 v[140:141], v[24:25], v[24:25]
	v_pk_fma_f32 v[140:141], v[26:27], v[26:27], v[140:141]
	v_add_f32_e32 v194, v194, v140
	v_add_f32_e32 v194, v194, v141
	v_pk_mul_f32 v[140:141], v[20:21], v[20:21]
	v_pk_fma_f32 v[140:141], v[22:23], v[22:23], v[140:141]
	v_add_f32_e32 v194, v194, v140
	v_add_f32_e32 v194, v194, v141
	v_pk_mul_f32 v[140:141], v[16:17], v[16:17]
	v_pk_fma_f32 v[140:141], v[18:19], v[18:19], v[140:141]
	v_add_f32_e32 v194, v194, v140
	v_add_f32_e32 v194, v194, v141
	s_waitcnt vmcnt(0)
	v_pk_mul_f32 v[14:15], v[14:15], v[242:243]
	v_pk_mul_f32 v[12:13], v[12:13], v[240:241]
	v_pk_add_f32 v[14:15], v[14:15], v[226:227]
	v_pk_add_f32 v[12:13], v[12:13], v[224:225]
	v_pk_mul_f32 v[10:11], v[10:11], v[246:247]
	v_pk_mul_f32 v[8:9], v[8:9], v[244:245]
	v_pk_add_f32 v[10:11], v[10:11], v[230:231]
	v_pk_add_f32 v[8:9], v[8:9], v[228:229]
	v_pk_mul_f32 v[6:7], v[6:7], v[250:251]
	v_pk_mul_f32 v[4:5], v[4:5], v[248:249]
	v_pk_add_f32 v[6:7], v[6:7], v[234:235]
	v_pk_add_f32 v[4:5], v[4:5], v[232:233]
	v_pk_mul_f32 v[2:3], v[2:3], v[186:187]
	v_pk_mul_f32 v[0:1], v[0:1], v[184:185]
	v_pk_add_f32 v[2:3], v[2:3], v[238:239]
	v_pk_add_f32 v[0:1], v[0:1], v[236:237]
	v_pk_mul_f32 v[140:141], v[12:13], v[12:13]
	v_pk_fma_f32 v[140:141], v[14:15], v[14:15], v[140:141]
	v_add_f32_e32 v195, v195, v140
	v_add_f32_e32 v195, v195, v141
	v_pk_mul_f32 v[140:141], v[8:9], v[8:9]
	v_pk_fma_f32 v[140:141], v[10:11], v[10:11], v[140:141]
	v_add_f32_e32 v195, v195, v140
	v_add_f32_e32 v195, v195, v141
	v_pk_mul_f32 v[140:141], v[4:5], v[4:5]
	v_pk_fma_f32 v[140:141], v[6:7], v[6:7], v[140:141]
	v_add_f32_e32 v195, v195, v140
	v_add_f32_e32 v195, v195, v141
	v_pk_mul_f32 v[140:141], v[0:1], v[0:1]
	v_pk_fma_f32 v[140:141], v[2:3], v[2:3], v[140:141]
	v_add_f32_e32 v195, v195, v140
	v_add_f32_e32 v195, v195, v141
	ds_swizzle_b32 v208, v188 offset:swizzle(SWAP,16)
	ds_swizzle_b32 v209, v189 offset:swizzle(SWAP,16)
	ds_swizzle_b32 v210, v190 offset:swizzle(SWAP,16)
	ds_swizzle_b32 v211, v191 offset:swizzle(SWAP,16)
	ds_swizzle_b32 v212, v192 offset:swizzle(SWAP,16)
	ds_swizzle_b32 v213, v193 offset:swizzle(SWAP,16)
	ds_swizzle_b32 v214, v194 offset:swizzle(SWAP,16)
	ds_swizzle_b32 v215, v195 offset:swizzle(SWAP,16)
	s_waitcnt lgkmcnt(0)
	v_add_f32_e32 v188, v188, v208
	v_add_f32_e32 v189, v189, v209
	v_add_f32_e32 v190, v190, v210
	v_add_f32_e32 v191, v191, v211
	v_add_f32_e32 v192, v192, v212
	v_add_f32_e32 v193, v193, v213
	v_add_f32_e32 v194, v194, v214
	v_add_f32_e32 v195, v195, v215
	v_mov_b32_e32 v208, v188
	v_mov_b32_e32 v209, v189
	v_mov_b32_e32 v210, v190
	v_mov_b32_e32 v211, v191
	v_mov_b32_e32 v212, v192
	v_mov_b32_e32 v213, v193
	v_mov_b32_e32 v214, v194
	v_mov_b32_e32 v215, v195
	s_nop 1
	v_permlane32_swap_b32 v188, v208
	v_permlane32_swap_b32 v189, v209
	v_permlane32_swap_b32 v190, v210
	v_permlane32_swap_b32 v191, v211
	v_permlane32_swap_b32 v192, v212
	v_permlane32_swap_b32 v193, v213
	v_permlane32_swap_b32 v194, v214
	v_permlane32_swap_b32 v195, v215
	s_nop 1
	v_add_f32_e32 v188, v188, v208
	v_add_f32_e32 v189, v189, v209
	v_add_f32_e32 v190, v190, v210
	v_add_f32_e32 v191, v191, v211
	v_add_f32_e32 v192, v192, v212
	v_add_f32_e32 v193, v193, v213
	v_add_f32_e32 v194, v194, v214
	v_add_f32_e32 v195, v195, v215
	v_readlane_b32 s25, v253, 2
	s_nop 3
	s_and_b32 s27, s25, 3
	s_lshl_b32 s27, s27, 10
	s_add_i32 s27, s27, 0x20800
	v_lshl_add_u32 v143, v142, 2, s27
	ds_write_b32 v143, v188
	ds_write_b32 v143, v189 offset:64
	ds_write_b32 v143, v190 offset:128
	ds_write_b32 v143, v191 offset:192
	ds_write_b32 v143, v192 offset:512
	ds_write_b32 v143, v193 offset:576
	ds_write_b32 v143, v194 offset:640
	ds_write_b32 v143, v195 offset:704
	v_mbcnt_lo_u32_b32 v207, -1, 0
	v_mbcnt_hi_u32_b32 v207, -1, v207
	s_lshl_b32 s27, s25, 6
	v_add_u32_e32 v207, s27, v207
	v_lshlrev_b32_e32 v207, 2, v207
	s_sub_u32 s70, s16, 0x7800000
	s_subb_u32 s71, s17, 0
	s_lshl_b32 s74, s4, 11
	s_add_u32 s70, s70, s74
	s_addc_u32 s71, s71, 0
	s_lshl_b32 s32, s96, 3
	s_add_i32 s32, s32, 4
	s_or_b32 s32, s32, 0xc0de0000
	s_waitcnt lgkmcnt(0)
	s_barrier
;     __device__ __forceinline__ void operator()(const Acc& acc, const Unit& u, int wr, int wc, int fr, int fq) const {
;     ...
;                         } else *(f32x4*)(X + (size_t)row * D + col) = *(const f32x4*)(base + col) + ga; } }
; template <bool FINAL>
; __device__ __forceinline__ void norm_rows(const float* xp, const float* xs, const float* X, const float* g, const float* sh, const float* sc, bf16_t* XN, float* out, int gw, int NGW, int lane, const float* part, int nsplit) {
;     ...
;         const float rstd = 1.0f / sqrtf(wave_sum(s) * (1.0f / D) + EPS);
;         const int mr = mod_row(row);
;         if (!FINAL && xp && row >= MP) {
; #pragma unroll
;             for (int j = 0; j < 4; ++j) *(f32x4*)((float*)X + (size_t)row * D + 4 * lane + 256 * j) = v[j]; }
; #pragma unroll
;         for (int j = 0; j < 4; ++j) { const int col = 4 * lane + 256 * j; const f32x4 gg = *(const f32x4*)(g + col);
;             if (FINAL) { *(f32x4*)(out + (size_t)row * D + col) = v[j] * rstd * gg; }
;             else { const f32x4 s1 = *(const f32x4*)(sc + (size_t)mr * 6144 + col), s0 = *(const f32x4*)(sh + (size_t)mr * 6144 + col);
	s_cmp_lt_u32 s25, 4
	s_cbranch_scc0 .Lfz_out_nopub
	v_add_u32_e32 v140, 0x20800, v207
	ds_read_b32 v212, v140
	ds_read_b32 v213, v140 offset:1024
	ds_read_b32 v214, v140 offset:2048
	ds_read_b32 v215, v140 offset:3072
	v_lshlrev_b32_e32 v188, 1, v207
	s_lshl_b32 s74, s36, 17
	v_add_u32_e32 v141, s74, v188
	s_waitcnt lgkmcnt(0)
	v_add_f32_e32 v212, v212, v213
	v_add_f32_e32 v212, v212, v214
	v_add_f32_e32 v212, v212, v215
	v_mov_b32_e32 v213, s32
	global_store_dwordx2 v141, v[212:213], s[70:71] sc0 sc1
.Lfz_out_nopub:
	v_mov_b32_e32 v140, 0x20450
	ds_read_b64 v[140:141], v140
	s_waitcnt lgkmcnt(0)
	v_readfirstlane_b32 s2, v140
	v_readfirstlane_b32 s3, v141
	s_add_i32 s74, s96, 0
	s_lshl_b32 s74, s74, 12
	s_add_u32 s2, s2, s74
	s_addc_u32 s3, s3, 0
	s_nop 4
	global_load_dwordx4 v[208:211], v159, s[2:3]
	global_load_dwordx4 v[212:215], v159, s[2:3] offset:64
	global_load_dwordx4 v[216:219], v159, s[2:3] offset:512
	global_load_dwordx4 v[220:223], v159, s[2:3] offset:576
	s_mov_b32 s74, 0x1000
	v_add_co_u32_e32 v130, vcc, s74, v130
	s_nop 1
	v_addc_co_u32_e32 v131, vcc, 0, v131, vcc
	global_load_dwordx4 v[240:243], v[130:131], off
	global_load_dwordx4 v[244:247], v[130:131], off offset:64
	global_load_dwordx4 v[248:251], v[130:131], off offset:512
	global_load_dwordx4 v[184:187], v[130:131], off offset:576
	v_add_co_u32_e32 v130, vcc, 0x1000, v130
	s_nop 1
	v_addc_co_u32_e32 v131, vcc, 0, v131, vcc
	global_load_dwordx4 v[224:227], v[130:131], off
	global_load_dwordx4 v[228:231], v[130:131], off offset:64
	global_load_dwordx4 v[232:235], v[130:131], off offset:512
	global_load_dwordx4 v[236:239], v[130:131], off offset:576
	global_store_dwordx4 v[146:147], v[124:127], off
	global_store_dwordx4 v[146:147], v[120:123], off offset:64
	global_store_dwordx4 v[146:147], v[116:119], off offset:512
	global_store_dwordx4 v[146:147], v[112:115], off offset:576
	v_lshl_add_u64 v[146:147], v[146:147], 0, s[66:67]
	global_store_dwordx4 v[146:147], v[108:111], off
	global_store_dwordx4 v[146:147], v[104:107], off offset:64
	global_store_dwordx4 v[146:147], v[100:103], off offset:512
	global_store_dwordx4 v[146:147], v[96:99], off offset:576
	v_lshl_add_u64 v[146:147], v[146:147], 0, s[66:67]
	global_store_dwordx4 v[146:147], v[92:95], off
	global_store_dwordx4 v[146:147], v[88:91], off offset:64
	global_store_dwordx4 v[146:147], v[84:87], off offset:512
	global_store_dwordx4 v[146:147], v[80:83], off offset:576
	v_lshl_add_u64 v[146:147], v[146:147], 0, s[66:67]
	global_store_dwordx4 v[146:147], v[76:79], off
	global_store_dwordx4 v[146:147], v[72:75], off offset:64
	global_store_dwordx4 v[146:147], v[68:71], off offset:512
	global_store_dwordx4 v[146:147], v[64:67], off offset:576
	v_lshl_add_u64 v[146:147], v[146:147], 0, s[68:69]
	global_store_dwordx4 v[146:147], v[60:63], off
	global_store_dwordx4 v[146:147], v[56:59], off offset:64
	global_store_dwordx4 v[146:147], v[52:55], off offset:512
	global_store_dwordx4 v[146:147], v[48:51], off offset:576
	v_lshl_add_u64 v[146:147], v[146:147], 0, s[66:67]
	global_store_dwordx4 v[146:147], v[44:47], off
	global_store_dwordx4 v[146:147], v[40:43], off offset:64
	global_store_dwordx4 v[146:147], v[36:39], off offset:512
	global_store_dwordx4 v[146:147], v[32:35], off offset:576
	v_lshl_add_u64 v[146:147], v[146:147], 0, s[66:67]
	global_store_dwordx4 v[146:147], v[28:31], off
	global_store_dwordx4 v[146:147], v[24:27], off offset:64
	global_store_dwordx4 v[146:147], v[20:23], off offset:512
	global_store_dwordx4 v[146:147], v[16:19], off offset:576
	v_lshl_add_u64 v[146:147], v[146:147], 0, s[66:67]
	global_store_dwordx4 v[146:147], v[12:15], off
	global_store_dwordx4 v[146:147], v[8:11], off offset:64
	global_store_dwordx4 v[146:147], v[4:7], off offset:512
	global_store_dwordx4 v[146:147], v[0:3], off offset:576
	s_cmp_lt_u32 s25, 4
	s_cbranch_scc0 .Lfz_out_norstd
	v_add_u32_e32 v189, 0x20000, v188
	v_add_u32_e32 v190, 0x40000, v188
	v_add_u32_e32 v191, 0x60000, v188
	s_mov_b32 s65, 0
.Lfz_out_poll:
	global_load_dwordx2 v[140:141], v188, s[70:71] sc0 sc1
	global_load_dwordx2 v[144:145], v189, s[70:71] sc0 sc1
	global_load_dwordx2 v[196:197], v190, s[70:71] sc0 sc1
	global_load_dwordx2 v[130:131], v191, s[70:71] sc0 sc1
	s_waitcnt vmcnt(0)
	v_cmp_eq_u32_e64 s[98:99], s32, v141
	v_cmp_eq_u32_e32 vcc, s32, v145
	s_and_b64 s[98:99], s[98:99], vcc
	v_cmp_eq_u32_e32 vcc, s32, v197
	s_and_b64 s[98:99], s[98:99], vcc
	v_cmp_eq_u32_e32 vcc, s32, v131
	s_and_b64 s[98:99], s[98:99], vcc
	s_andn2_b64 exec, exec, s[98:99]
	s_cbranch_execz .Lfz_out_polled
	s_add_i32 s65, s65, 1
	s_cmp_lt_u32 s65, 0x8000
	s_cbranch_scc0 .Lfz_out_polled
	s_sleep 1
	s_branch .Lfz_out_poll
.Lfz_out_polled:
	s_mov_b64 exec, -1
	v_add_f32_e32 v140, v140, v144
	v_add_f32_e32 v140, v140, v196
	v_add_f32_e32 v140, v140, v130
	v_mov_b32_e32 v192, 0x358637bd
	v_fmamk_f32 v140, v140, 0x3a800000, v192
	v_mul_f32_e32 v145, 0x4f800000, v140
	v_cmp_gt_f32_e32 vcc, 0xf800000, v140
	s_nop 1
	v_cndmask_b32_e32 v140, v140, v145, vcc
	v_sqrt_f32_e32 v145, v140
	s_nop 0
	v_add_u32_e32 v197, -1, v145
	v_add_u32_e32 v131, 1, v145
	v_fma_f32 v159, -v197, v145, v140
	v_fma_f32 v192, -v131, v145, v140
	v_cmp_ge_f32_e64 s[98:99], 0, v159
	s_nop 1
	v_cndmask_b32_e64 v145, v145, v197, s[98:99]
	v_cmp_lt_f32_e64 s[98:99], 0, v192
	s_nop 1
	v_cndmask_b32_e64 v145, v145, v131, s[98:99]
	v_mul_f32_e32 v197, 0x37800000, v145
	v_cndmask_b32_e32 v145, v145, v197, vcc
	v_mov_b32_e32 v197, 0x260
	v_cmp_class_f32_e32 vcc, v140, v197
	s_nop 1
	v_cndmask_b32_e32 v140, v145, v140, vcc
	v_div_scale_f32 v145, s[98:99], v140, v140, 1.0
	v_rcp_f32_e32 v197, v145
	v_div_scale_f32 v131, vcc, 1.0, v140, 1.0
	s_nop 0
	v_fma_f32 v159, -v145, v197, 1.0
	v_fmac_f32_e32 v197, v159, v197
	v_mul_f32_e32 v159, v131, v197
	v_fma_f32 v192, -v145, v159, v131
	v_fmac_f32_e32 v159, v192, v197
	v_fma_f32 v145, -v145, v159, v131
	v_div_fmas_f32 v145, v145, v197, v159
	v_div_fixup_f32 v145, v145, v140, 1.0
	v_add_u32_e32 v197, 0x21800, v207
	ds_write_b32 v197, v145
; __device__ __forceinline__ unsigned cvt_pk_bf16(float lo, float hi) { const f32x2_t v = {lo, hi}; const bf16x2_t b = __builtin_convertvector(v, bf16x2_t); return __builtin_bit_cast(unsigned, b); }
; template <bool FINAL>
; __device__ __forceinline__ void norm_rows(const float* xp, const float* xs, const float* X, const float* g, const float* sh, const float* sc, bf16_t* XN, float* out, int gw, int NGW, int lane, const float* part, int nsplit) {
;     ...
;         for (int j = 0; j < 4; ++j) { const int col = 4 * lane + 256 * j; const f32x4 gg = *(const f32x4*)(g + col);
;             if (FINAL) { *(f32x4*)(out + (size_t)row * D + col) = v[j] * rstd * gg; }
;             else { const f32x4 s1 = *(const f32x4*)(sc + (size_t)mr * 6144 + col), s0 = *(const f32x4*)(sh + (size_t)mr * 6144 + col);
;                 const f32x4 h = v[j] * rstd * gg * (s1 + 1.0f) + s0;
;                 *(u32x2*)(XN + (size_t)row * D + col) = (u32x2){cvt_pk_bf16(h[0], h[1]), cvt_pk_bf16(h[2], h[3])}; } }
.Lfz_out_norstd:
	s_waitcnt lgkmcnt(0)
	s_barrier
	v_lshlrev_b32_e32 v145, 2, v142
	v_add_u32_e32 v145, 0x21800, v145
	ds_read_b32 v188, v145
	ds_read_b32 v189, v145 offset:64
	ds_read_b32 v190, v145 offset:128
	ds_read_b32 v191, v145 offset:192
	ds_read_b32 v192, v145 offset:512
	ds_read_b32 v193, v145 offset:576
	ds_read_b32 v194, v145 offset:640
	ds_read_b32 v195, v145 offset:704
	s_waitcnt vmcnt(0) lgkmcnt(0)
	v_pk_add_f32 v[226:227], v[226:227], 1.0 op_sel_hi:[1,0]
	v_pk_add_f32 v[224:225], v[224:225], 1.0 op_sel_hi:[1,0]
	v_pk_add_f32 v[230:231], v[230:231], 1.0 op_sel_hi:[1,0]
	v_pk_add_f32 v[228:229], v[228:229], 1.0 op_sel_hi:[1,0]
	v_pk_add_f32 v[234:235], v[234:235], 1.0 op_sel_hi:[1,0]
	v_pk_add_f32 v[232:233], v[232:233], 1.0 op_sel_hi:[1,0]
	v_pk_add_f32 v[238:239], v[238:239], 1.0 op_sel_hi:[1,0]
	v_pk_add_f32 v[236:237], v[236:237], 1.0 op_sel_hi:[1,0]
	v_mul_f32_e32 v124, v124, v188
	v_mul_f32_e32 v125, v125, v188
	v_mul_f32_e32 v126, v126, v188
	v_mul_f32_e32 v127, v127, v188
	v_pk_mul_f32 v[124:125], v[208:209], v[124:125]
	v_pk_mul_f32 v[126:127], v[210:211], v[126:127]
	v_pk_fma_f32 v[126:127], v[226:227], v[126:127], v[242:243]
	v_pk_fma_f32 v[124:125], v[224:225], v[124:125], v[240:241]
	s_nop 0
	v_cvt_pk_bf16_f32 v124, v124, v125
	v_cvt_pk_bf16_f32 v125, v126, v127
	global_store_dwordx2 v[128:129], v[124:125], off
	v_mul_f32_e32 v120, v120, v188
	v_mul_f32_e32 v121, v121, v188
	v_mul_f32_e32 v122, v122, v188
	v_mul_f32_e32 v123, v123, v188
	v_pk_mul_f32 v[120:121], v[212:213], v[120:121]
	v_pk_mul_f32 v[122:123], v[214:215], v[122:123]
	v_pk_fma_f32 v[122:123], v[230:231], v[122:123], v[246:247]
	v_pk_fma_f32 v[120:121], v[228:229], v[120:121], v[244:245]
	s_nop 0
	v_cvt_pk_bf16_f32 v120, v120, v121
	v_cvt_pk_bf16_f32 v121, v122, v123
	global_store_dwordx2 v[128:129], v[120:121], off offset:32
	v_mul_f32_e32 v116, v116, v188
	v_mul_f32_e32 v117, v117, v188
	v_mul_f32_e32 v118, v118, v188
	v_mul_f32_e32 v119, v119, v188
	v_pk_mul_f32 v[116:117], v[216:217], v[116:117]
	v_pk_mul_f32 v[118:119], v[218:219], v[118:119]
	v_pk_fma_f32 v[118:119], v[234:235], v[118:119], v[250:251]
	v_pk_fma_f32 v[116:117], v[232:233], v[116:117], v[248:249]
	s_nop 0
	v_cvt_pk_bf16_f32 v116, v116, v117
	v_cvt_pk_bf16_f32 v117, v118, v119
	global_store_dwordx2 v[128:129], v[116:117], off offset:256
	v_mul_f32_e32 v112, v112, v188
	v_mul_f32_e32 v113, v113, v188
	v_mul_f32_e32 v114, v114, v188
	v_mul_f32_e32 v115, v115, v188
	v_pk_mul_f32 v[112:113], v[220:221], v[112:113]
	v_pk_mul_f32 v[114:115], v[222:223], v[114:115]
	v_pk_fma_f32 v[114:115], v[238:239], v[114:115], v[186:187]
	v_pk_fma_f32 v[112:113], v[236:237], v[112:113], v[184:185]
	s_nop 0
	v_cvt_pk_bf16_f32 v112, v112, v113
	v_cvt_pk_bf16_f32 v113, v114, v115
	global_store_dwordx2 v[128:129], v[112:113], off offset:288
	v_add_co_u32_e32 v128, vcc, 0x8000, v128
	s_nop 1
	v_addc_co_u32_e32 v129, vcc, 0, v129, vcc
	v_mul_f32_e32 v108, v108, v189
	v_mul_f32_e32 v109, v109, v189
	v_mul_f32_e32 v110, v110, v189
	v_mul_f32_e32 v111, v111, v189
	v_pk_mul_f32 v[108:109], v[208:209], v[108:109]
	v_pk_mul_f32 v[110:111], v[210:211], v[110:111]
	v_pk_fma_f32 v[110:111], v[226:227], v[110:111], v[242:243]
	v_pk_fma_f32 v[108:109], v[224:225], v[108:109], v[240:241]
	s_nop 0
	v_cvt_pk_bf16_f32 v108, v108, v109
	v_cvt_pk_bf16_f32 v109, v110, v111
	global_store_dwordx2 v[128:129], v[108:109], off
	v_mul_f32_e32 v104, v104, v189
	v_mul_f32_e32 v105, v105, v189
	v_mul_f32_e32 v106, v106, v189
	v_mul_f32_e32 v107, v107, v189
	v_pk_mul_f32 v[104:105], v[212:213], v[104:105]
	v_pk_mul_f32 v[106:107], v[214:215], v[106:107]
	v_pk_fma_f32 v[106:107], v[230:231], v[106:107], v[246:247]
	v_pk_fma_f32 v[104:105], v[228:229], v[104:105], v[244:245]
	s_nop 0
	v_cvt_pk_bf16_f32 v104, v104, v105
	v_cvt_pk_bf16_f32 v105, v106, v107
	global_store_dwordx2 v[128:129], v[104:105], off offset:32
	v_mul_f32_e32 v100, v100, v189
	v_mul_f32_e32 v101, v101, v189
	v_mul_f32_e32 v102, v102, v189
	v_mul_f32_e32 v103, v103, v189
	v_pk_mul_f32 v[100:101], v[216:217], v[100:101]
	v_pk_mul_f32 v[102:103], v[218:219], v[102:103]
	v_pk_fma_f32 v[102:103], v[234:235], v[102:103], v[250:251]
	v_pk_fma_f32 v[100:101], v[232:233], v[100:101], v[248:249]
	s_nop 0
	v_cvt_pk_bf16_f32 v100, v100, v101
	v_cvt_pk_bf16_f32 v101, v102, v103
	global_store_dwordx2 v[128:129], v[100:101], off offset:256
	v_mul_f32_e32 v96, v96, v189
	v_mul_f32_e32 v97, v97, v189
	v_mul_f32_e32 v98, v98, v189
	v_mul_f32_e32 v99, v99, v189
	v_pk_mul_f32 v[96:97], v[220:221], v[96:97]
	v_pk_mul_f32 v[98:99], v[222:223], v[98:99]
	v_pk_fma_f32 v[98:99], v[238:239], v[98:99], v[186:187]
	v_pk_fma_f32 v[96:97], v[236:237], v[96:97], v[184:185]
	s_nop 0
	v_cvt_pk_bf16_f32 v96, v96, v97
	v_cvt_pk_bf16_f32 v97, v98, v99
	global_store_dwordx2 v[128:129], v[96:97], off offset:288
	v_add_co_u32_e32 v128, vcc, 0x8000, v128
	s_nop 1
	v_addc_co_u32_e32 v129, vcc, 0, v129, vcc
	v_mul_f32_e32 v92, v92, v190
	v_mul_f32_e32 v93, v93, v190
	v_mul_f32_e32 v94, v94, v190
	v_mul_f32_e32 v95, v95, v190
	v_pk_mul_f32 v[92:93], v[208:209], v[92:93]
	v_pk_mul_f32 v[94:95], v[210:211], v[94:95]
	v_pk_fma_f32 v[94:95], v[226:227], v[94:95], v[242:243]
	v_pk_fma_f32 v[92:93], v[224:225], v[92:93], v[240:241]
	s_nop 0
	v_cvt_pk_bf16_f32 v92, v92, v93
	v_cvt_pk_bf16_f32 v93, v94, v95
	global_store_dwordx2 v[128:129], v[92:93], off
	v_mul_f32_e32 v88, v88, v190
	v_mul_f32_e32 v89, v89, v190
	v_mul_f32_e32 v90, v90, v190
	v_mul_f32_e32 v91, v91, v190
	v_pk_mul_f32 v[88:89], v[212:213], v[88:89]
	v_pk_mul_f32 v[90:91], v[214:215], v[90:91]
	v_pk_fma_f32 v[90:91], v[230:231], v[90:91], v[246:247]
; __device__ __forceinline__ unsigned cvt_pk_bf16(float lo, float hi) { const f32x2_t v = {lo, hi}; const bf16x2_t b = __builtin_convertvector(v, bf16x2_t); return __builtin_bit_cast(unsigned, b); }
; template <bool FINAL>
; __device__ __forceinline__ void norm_rows(const float* xp, const float* xs, const float* X, const float* g, const float* sh, const float* sc, bf16_t* XN, float* out, int gw, int NGW, int lane, const float* part, int nsplit) {
;     ...
;         for (int j = 0; j < 4; ++j) { const int col = 4 * lane + 256 * j; const f32x4 gg = *(const f32x4*)(g + col);
;             if (FINAL) { *(f32x4*)(out + (size_t)row * D + col) = v[j] * rstd * gg; }
;             else { const f32x4 s1 = *(const f32x4*)(sc + (size_t)mr * 6144 + col), s0 = *(const f32x4*)(sh + (size_t)mr * 6144 + col);
;                 const f32x4 h = v[j] * rstd * gg * (s1 + 1.0f) + s0;
;                 *(u32x2*)(XN + (size_t)row * D + col) = (u32x2){cvt_pk_bf16(h[0], h[1]), cvt_pk_bf16(h[2], h[3])}; } }
	v_pk_fma_f32 v[88:89], v[228:229], v[88:89], v[244:245]
	s_nop 0
	v_cvt_pk_bf16_f32 v88, v88, v89
	v_cvt_pk_bf16_f32 v89, v90, v91
	global_store_dwordx2 v[128:129], v[88:89], off offset:32
	v_mul_f32_e32 v84, v84, v190
	v_mul_f32_e32 v85, v85, v190
	v_mul_f32_e32 v86, v86, v190
	v_mul_f32_e32 v87, v87, v190
	v_pk_mul_f32 v[84:85], v[216:217], v[84:85]
	v_pk_mul_f32 v[86:87], v[218:219], v[86:87]
	v_pk_fma_f32 v[86:87], v[234:235], v[86:87], v[250:251]
	v_pk_fma_f32 v[84:85], v[232:233], v[84:85], v[248:249]
	s_nop 0
	v_cvt_pk_bf16_f32 v84, v84, v85
	v_cvt_pk_bf16_f32 v85, v86, v87
	global_store_dwordx2 v[128:129], v[84:85], off offset:256
	v_mul_f32_e32 v80, v80, v190
	v_mul_f32_e32 v81, v81, v190
	v_mul_f32_e32 v82, v82, v190
	v_mul_f32_e32 v83, v83, v190
	v_pk_mul_f32 v[80:81], v[220:221], v[80:81]
	v_pk_mul_f32 v[82:83], v[222:223], v[82:83]
	v_pk_fma_f32 v[82:83], v[238:239], v[82:83], v[186:187]
	v_pk_fma_f32 v[80:81], v[236:237], v[80:81], v[184:185]
	s_nop 0
	v_cvt_pk_bf16_f32 v80, v80, v81
	v_cvt_pk_bf16_f32 v81, v82, v83
	global_store_dwordx2 v[128:129], v[80:81], off offset:288
	v_add_co_u32_e32 v128, vcc, 0x8000, v128
	s_nop 1
	v_addc_co_u32_e32 v129, vcc, 0, v129, vcc
	v_mul_f32_e32 v76, v76, v191
	v_mul_f32_e32 v77, v77, v191
	v_mul_f32_e32 v78, v78, v191
	v_mul_f32_e32 v79, v79, v191
	v_pk_mul_f32 v[76:77], v[208:209], v[76:77]
	v_pk_mul_f32 v[78:79], v[210:211], v[78:79]
	v_pk_fma_f32 v[78:79], v[226:227], v[78:79], v[242:243]
	v_pk_fma_f32 v[76:77], v[224:225], v[76:77], v[240:241]
	s_nop 0
	v_cvt_pk_bf16_f32 v76, v76, v77
	v_cvt_pk_bf16_f32 v77, v78, v79
	global_store_dwordx2 v[128:129], v[76:77], off
	v_mul_f32_e32 v72, v72, v191
	v_mul_f32_e32 v73, v73, v191
	v_mul_f32_e32 v74, v74, v191
	v_mul_f32_e32 v75, v75, v191
	v_pk_mul_f32 v[72:73], v[212:213], v[72:73]
	v_pk_mul_f32 v[74:75], v[214:215], v[74:75]
	v_pk_fma_f32 v[74:75], v[230:231], v[74:75], v[246:247]
	v_pk_fma_f32 v[72:73], v[228:229], v[72:73], v[244:245]
	s_nop 0
	v_cvt_pk_bf16_f32 v72, v72, v73
	v_cvt_pk_bf16_f32 v73, v74, v75
	global_store_dwordx2 v[128:129], v[72:73], off offset:32
	v_mul_f32_e32 v68, v68, v191
	v_mul_f32_e32 v69, v69, v191
	v_mul_f32_e32 v70, v70, v191
	v_mul_f32_e32 v71, v71, v191
	v_pk_mul_f32 v[68:69], v[216:217], v[68:69]
	v_pk_mul_f32 v[70:71], v[218:219], v[70:71]
	v_pk_fma_f32 v[70:71], v[234:235], v[70:71], v[250:251]
	v_pk_fma_f32 v[68:69], v[232:233], v[68:69], v[248:249]
	s_nop 0
	v_cvt_pk_bf16_f32 v68, v68, v69
	v_cvt_pk_bf16_f32 v69, v70, v71
	global_store_dwordx2 v[128:129], v[68:69], off offset:256
	v_mul_f32_e32 v64, v64, v191
	v_mul_f32_e32 v65, v65, v191
	v_mul_f32_e32 v66, v66, v191
	v_mul_f32_e32 v67, v67, v191
	v_pk_mul_f32 v[64:65], v[220:221], v[64:65]
	v_pk_mul_f32 v[66:67], v[222:223], v[66:67]
	v_pk_fma_f32 v[66:67], v[238:239], v[66:67], v[186:187]
	v_pk_fma_f32 v[64:65], v[236:237], v[64:65], v[184:185]
	s_nop 0
	v_cvt_pk_bf16_f32 v64, v64, v65
	v_cvt_pk_bf16_f32 v65, v66, v67
	global_store_dwordx2 v[128:129], v[64:65], off offset:288
	v_add_co_u32_e32 v128, vcc, 0x28000, v128
	s_nop 1
	v_addc_co_u32_e32 v129, vcc, 0, v129, vcc
	v_mul_f32_e32 v60, v60, v192
	v_mul_f32_e32 v61, v61, v192
	v_mul_f32_e32 v62, v62, v192
	v_mul_f32_e32 v63, v63, v192
	v_pk_mul_f32 v[60:61], v[208:209], v[60:61]
	v_pk_mul_f32 v[62:63], v[210:211], v[62:63]
	v_pk_fma_f32 v[62:63], v[226:227], v[62:63], v[242:243]
	v_pk_fma_f32 v[60:61], v[224:225], v[60:61], v[240:241]
	s_nop 0
	v_cvt_pk_bf16_f32 v60, v60, v61
	v_cvt_pk_bf16_f32 v61, v62, v63
	global_store_dwordx2 v[128:129], v[60:61], off
	v_mul_f32_e32 v56, v56, v192
	v_mul_f32_e32 v57, v57, v192
	v_mul_f32_e32 v58, v58, v192
	v_mul_f32_e32 v59, v59, v192
	v_pk_mul_f32 v[56:57], v[212:213], v[56:57]
	v_pk_mul_f32 v[58:59], v[214:215], v[58:59]
	v_pk_fma_f32 v[58:59], v[230:231], v[58:59], v[246:247]
	v_pk_fma_f32 v[56:57], v[228:229], v[56:57], v[244:245]
	s_nop 0
	v_cvt_pk_bf16_f32 v56, v56, v57
	v_cvt_pk_bf16_f32 v57, v58, v59
	global_store_dwordx2 v[128:129], v[56:57], off offset:32
	v_mul_f32_e32 v52, v52, v192
	v_mul_f32_e32 v53, v53, v192
	v_mul_f32_e32 v54, v54, v192
	v_mul_f32_e32 v55, v55, v192
	v_pk_mul_f32 v[52:53], v[216:217], v[52:53]
	v_pk_mul_f32 v[54:55], v[218:219], v[54:55]
	v_pk_fma_f32 v[54:55], v[234:235], v[54:55], v[250:251]
	v_pk_fma_f32 v[52:53], v[232:233], v[52:53], v[248:249]
	s_nop 0
	v_cvt_pk_bf16_f32 v52, v52, v53
	v_cvt_pk_bf16_f32 v53, v54, v55
	global_store_dwordx2 v[128:129], v[52:53], off offset:256
	v_mul_f32_e32 v48, v48, v192
	v_mul_f32_e32 v49, v49, v192
	v_mul_f32_e32 v50, v50, v192
	v_mul_f32_e32 v51, v51, v192
	v_pk_mul_f32 v[48:49], v[220:221], v[48:49]
	v_pk_mul_f32 v[50:51], v[222:223], v[50:51]
	v_pk_fma_f32 v[50:51], v[238:239], v[50:51], v[186:187]
	v_pk_fma_f32 v[48:49], v[236:237], v[48:49], v[184:185]
	s_nop 0
	v_cvt_pk_bf16_f32 v48, v48, v49
	v_cvt_pk_bf16_f32 v49, v50, v51
	global_store_dwordx2 v[128:129], v[48:49], off offset:288
	v_add_co_u32_e32 v128, vcc, 0x8000, v128
	s_nop 1
	v_addc_co_u32_e32 v129, vcc, 0, v129, vcc
	v_mul_f32_e32 v44, v44, v193
	v_mul_f32_e32 v45, v45, v193
	v_mul_f32_e32 v46, v46, v193
	v_mul_f32_e32 v47, v47, v193
	v_pk_mul_f32 v[44:45], v[208:209], v[44:45]
	v_pk_mul_f32 v[46:47], v[210:211], v[46:47]
	v_pk_fma_f32 v[46:47], v[226:227], v[46:47], v[242:243]
; __device__ __forceinline__ unsigned cvt_pk_bf16(float lo, float hi) { const f32x2_t v = {lo, hi}; const bf16x2_t b = __builtin_convertvector(v, bf16x2_t); return __builtin_bit_cast(unsigned, b); }
; template <bool FINAL>
; __device__ __forceinline__ void norm_rows(const float* xp, const float* xs, const float* X, const float* g, const float* sh, const float* sc, bf16_t* XN, float* out, int gw, int NGW, int lane, const float* part, int nsplit) {
;     ...
;         for (int j = 0; j < 4; ++j) { const int col = 4 * lane + 256 * j; const f32x4 gg = *(const f32x4*)(g + col);
;             if (FINAL) { *(f32x4*)(out + (size_t)row * D + col) = v[j] * rstd * gg; }
;             else { const f32x4 s1 = *(const f32x4*)(sc + (size_t)mr * 6144 + col), s0 = *(const f32x4*)(sh + (size_t)mr * 6144 + col);
;                 const f32x4 h = v[j] * rstd * gg * (s1 + 1.0f) + s0;
;                 *(u32x2*)(XN + (size_t)row * D + col) = (u32x2){cvt_pk_bf16(h[0], h[1]), cvt_pk_bf16(h[2], h[3])}; } }
	v_pk_fma_f32 v[44:45], v[224:225], v[44:45], v[240:241]
	s_nop 0
	v_cvt_pk_bf16_f32 v44, v44, v45
	v_cvt_pk_bf16_f32 v45, v46, v47
	global_store_dwordx2 v[128:129], v[44:45], off
	v_mul_f32_e32 v40, v40, v193
	v_mul_f32_e32 v41, v41, v193
	v_mul_f32_e32 v42, v42, v193
	v_mul_f32_e32 v43, v43, v193
	v_pk_mul_f32 v[40:41], v[212:213], v[40:41]
	v_pk_mul_f32 v[42:43], v[214:215], v[42:43]
	v_pk_fma_f32 v[42:43], v[230:231], v[42:43], v[246:247]
	v_pk_fma_f32 v[40:41], v[228:229], v[40:41], v[244:245]
	s_nop 0
	v_cvt_pk_bf16_f32 v40, v40, v41
	v_cvt_pk_bf16_f32 v41, v42, v43
	global_store_dwordx2 v[128:129], v[40:41], off offset:32
	v_mul_f32_e32 v36, v36, v193
	v_mul_f32_e32 v37, v37, v193
	v_mul_f32_e32 v38, v38, v193
	v_mul_f32_e32 v39, v39, v193
	v_pk_mul_f32 v[36:37], v[216:217], v[36:37]
	v_pk_mul_f32 v[38:39], v[218:219], v[38:39]
	v_pk_fma_f32 v[38:39], v[234:235], v[38:39], v[250:251]
	v_pk_fma_f32 v[36:37], v[232:233], v[36:37], v[248:249]
	s_nop 0
	v_cvt_pk_bf16_f32 v36, v36, v37
	v_cvt_pk_bf16_f32 v37, v38, v39
	global_store_dwordx2 v[128:129], v[36:37], off offset:256
	v_mul_f32_e32 v32, v32, v193
	v_mul_f32_e32 v33, v33, v193
	v_mul_f32_e32 v34, v34, v193
	v_mul_f32_e32 v35, v35, v193
	v_pk_mul_f32 v[32:33], v[220:221], v[32:33]
	v_pk_mul_f32 v[34:35], v[222:223], v[34:35]
	v_pk_fma_f32 v[34:35], v[238:239], v[34:35], v[186:187]
	v_pk_fma_f32 v[32:33], v[236:237], v[32:33], v[184:185]
	s_nop 0
	v_cvt_pk_bf16_f32 v32, v32, v33
	v_cvt_pk_bf16_f32 v33, v34, v35
	global_store_dwordx2 v[128:129], v[32:33], off offset:288
	v_add_co_u32_e32 v128, vcc, 0x8000, v128
	s_nop 1
	v_addc_co_u32_e32 v129, vcc, 0, v129, vcc
	v_mul_f32_e32 v28, v28, v194
	v_mul_f32_e32 v29, v29, v194
	v_mul_f32_e32 v30, v30, v194
	v_mul_f32_e32 v31, v31, v194
	v_pk_mul_f32 v[28:29], v[208:209], v[28:29]
	v_pk_mul_f32 v[30:31], v[210:211], v[30:31]
	v_pk_fma_f32 v[30:31], v[226:227], v[30:31], v[242:243]
	v_pk_fma_f32 v[28:29], v[224:225], v[28:29], v[240:241]
	s_nop 0
	v_cvt_pk_bf16_f32 v28, v28, v29
	v_cvt_pk_bf16_f32 v29, v30, v31
	global_store_dwordx2 v[128:129], v[28:29], off
	v_mul_f32_e32 v24, v24, v194
	v_mul_f32_e32 v25, v25, v194
	v_mul_f32_e32 v26, v26, v194
	v_mul_f32_e32 v27, v27, v194
	v_pk_mul_f32 v[24:25], v[212:213], v[24:25]
	v_pk_mul_f32 v[26:27], v[214:215], v[26:27]
	v_pk_fma_f32 v[26:27], v[230:231], v[26:27], v[246:247]
	v_pk_fma_f32 v[24:25], v[228:229], v[24:25], v[244:245]
	s_nop 0
	v_cvt_pk_bf16_f32 v24, v24, v25
	v_cvt_pk_bf16_f32 v25, v26, v27
	global_store_dwordx2 v[128:129], v[24:25], off offset:32
	v_mul_f32_e32 v20, v20, v194
	v_mul_f32_e32 v21, v21, v194
	v_mul_f32_e32 v22, v22, v194
	v_mul_f32_e32 v23, v23, v194
	v_pk_mul_f32 v[20:21], v[216:217], v[20:21]
	v_pk_mul_f32 v[22:23], v[218:219], v[22:23]
	v_pk_fma_f32 v[22:23], v[234:235], v[22:23], v[250:251]
	v_pk_fma_f32 v[20:21], v[232:233], v[20:21], v[248:249]
	s_nop 0
	v_cvt_pk_bf16_f32 v20, v20, v21
	v_cvt_pk_bf16_f32 v21, v22, v23
	global_store_dwordx2 v[128:129], v[20:21], off offset:256
	v_mul_f32_e32 v16, v16, v194
	v_mul_f32_e32 v17, v17, v194
	v_mul_f32_e32 v18, v18, v194
	v_mul_f32_e32 v19, v19, v194
	v_pk_mul_f32 v[16:17], v[220:221], v[16:17]
	v_pk_mul_f32 v[18:19], v[222:223], v[18:19]
	v_pk_fma_f32 v[18:19], v[238:239], v[18:19], v[186:187]
	v_pk_fma_f32 v[16:17], v[236:237], v[16:17], v[184:185]
	s_nop 0
	v_cvt_pk_bf16_f32 v16, v16, v17
	v_cvt_pk_bf16_f32 v17, v18, v19
	global_store_dwordx2 v[128:129], v[16:17], off offset:288
	v_add_co_u32_e32 v128, vcc, 0x8000, v128
	s_nop 1
	v_addc_co_u32_e32 v129, vcc, 0, v129, vcc
	v_mul_f32_e32 v12, v12, v195
	v_mul_f32_e32 v13, v13, v195
	v_mul_f32_e32 v14, v14, v195
	v_mul_f32_e32 v15, v15, v195
	v_pk_mul_f32 v[12:13], v[208:209], v[12:13]
	v_pk_mul_f32 v[14:15], v[210:211], v[14:15]
	v_pk_fma_f32 v[14:15], v[226:227], v[14:15], v[242:243]
	v_pk_fma_f32 v[12:13], v[224:225], v[12:13], v[240:241]
	s_nop 0
	v_cvt_pk_bf16_f32 v12, v12, v13
	v_cvt_pk_bf16_f32 v13, v14, v15
	global_store_dwordx2 v[128:129], v[12:13], off
	v_mul_f32_e32 v8, v8, v195
	v_mul_f32_e32 v9, v9, v195
	v_mul_f32_e32 v10, v10, v195
	v_mul_f32_e32 v11, v11, v195
	v_pk_mul_f32 v[8:9], v[212:213], v[8:9]
	v_pk_mul_f32 v[10:11], v[214:215], v[10:11]
	v_pk_fma_f32 v[10:11], v[230:231], v[10:11], v[246:247]
	v_pk_fma_f32 v[8:9], v[228:229], v[8:9], v[244:245]
	s_nop 0
	v_cvt_pk_bf16_f32 v8, v8, v9
	v_cvt_pk_bf16_f32 v9, v10, v11
	global_store_dwordx2 v[128:129], v[8:9], off offset:32
	v_mul_f32_e32 v4, v4, v195
	v_mul_f32_e32 v5, v5, v195
	v_mul_f32_e32 v6, v6, v195
	v_mul_f32_e32 v7, v7, v195
	v_pk_mul_f32 v[4:5], v[216:217], v[4:5]
	v_pk_mul_f32 v[6:7], v[218:219], v[6:7]
	v_pk_fma_f32 v[6:7], v[234:235], v[6:7], v[250:251]
	v_pk_fma_f32 v[4:5], v[232:233], v[4:5], v[248:249]
	s_nop 0
	v_cvt_pk_bf16_f32 v4, v4, v5
	v_cvt_pk_bf16_f32 v5, v6, v7
	global_store_dwordx2 v[128:129], v[4:5], off offset:256
	v_mul_f32_e32 v0, v0, v195
	v_mul_f32_e32 v1, v1, v195
	v_mul_f32_e32 v2, v2, v195
	v_mul_f32_e32 v3, v3, v195
	v_pk_mul_f32 v[0:1], v[220:221], v[0:1]
	v_pk_mul_f32 v[2:3], v[222:223], v[2:3]
	v_pk_fma_f32 v[2:3], v[238:239], v[2:3], v[186:187]
	v_pk_fma_f32 v[0:1], v[236:237], v[0:1], v[184:185]
	s_nop 0
	v_cvt_pk_bf16_f32 v0, v0, v1
	v_cvt_pk_bf16_f32 v1, v2, v3
	global_store_dwordx2 v[128:129], v[0:1], off offset:288
	s_branch .Lepi_out_done

;     __device__ __forceinline__ void operator()(const Acc& acc, const Unit& u, int wr, int wc, int fr, int fq) const {
; #pragma unroll
;         for (int ai = 0; ai < 2; ++ai)
; #pragma unroll
;             for (int m = 0; m < 4; ++m) { const int row = u.pm * 256 + ai * 128 + wr * 64 + m * 16 + fr;
;                 const float* base = xp ? (row < MP ? xp + (size_t)row * D : xs + (size_t)(row - MP) * D) : X + (size_t)row * D;
;                 const float* gp = gate + (size_t)mod_row(row) * 6144;
; #pragma unroll
;                 for (int bj = 0; bj < 2; ++bj)
; #pragma unroll
;                     for (int n = 0; n < 2; ++n) { const int col = u.pn * 256 + bj * 128 + wc * 32 + n * 16 + fq * 4;
;                         const f32x4 ga = *(const f32x4*)(gp + col) * acc[ai][bj][m][n];
;                         if (u.split) { *(f32x4*)(part + ((size_t)(u.k0 >> 8) * MS + (row - MP)) * D + col) = ga;
;                         } else *(f32x4*)(X + (size_t)row * D + col) = *(const f32x4*)(base + col) + ga; } }
; __global__ void __launch_bounds__(512, 2) hybrid_fwd(Params P) {
;     ...
;             EpiRes E{nullptr, nullptr, X, (MOD + (size_t)l * NMODROWS * 6144) + 5120, (float*)(ws + WS_PART)};
.LBB0_1882:
	s_lshl_b32 s2, s55, 8
	s_add_i32 s2, s2, s43
	s_lshl_b32 s3, s53, 8
	s_add_i32 s3, s3, s44
	v_add_u32_e32 v207, s2, v151
	v_lshl_add_u32 v159, v152, 2, s3
	v_mov_b32_e32 v197, 0
	s_mov_b32 s70, 0x10000
	s_mov_b32 s71, 0
	s_mov_b32 s98, 0x50000
	s_mov_b32 s99, 0
	s_cmp_lg_u32 s54, 0
	s_cbranch_scc1 .Lepi_dn_split
	s_cmp_eq_u32 s96, 3
	s_cbranch_scc1 .Lepi_dn_final
	s_mov_b32 s66, 0x10000
	s_mov_b32 s67, 0
	s_mov_b32 s68, 0x50000
	s_mov_b32 s69, 0
	v_lshlrev_b32_e32 v140, 11, v207
	v_lshl_add_u32 v140, v159, 1, v140
	v_mov_b32_e32 v141, 0
	s_add_u32 s70, s10, 0x4200000
	s_addc_u32 s71, s11, 0
	v_lshl_add_u64 v[128:129], v[140:141], 0, s[70:71]
	v_lshlrev_b32_e32 v196, 12, v207
	v_lshl_add_u32 v196, v159, 2, v196
	v_add_u32_e32 v142, s43, v151
	v_lshrrev_b32_e32 v207, 12, v207
	v_lshlrev_b32_e32 v159, 2, v159
	v_mad_u32_u24 v130, v207, s80, v159
	v_mov_b32_e32 v131, 0
	v_lshl_add_u64 v[130:131], v[130:131], 0, s[12:13]
	global_load_dwordx4 v[240:243], v[130:131], off
	global_load_dwordx4 v[244:247], v[130:131], off offset:64
	global_load_dwordx4 v[248:251], v[130:131], off offset:512
	global_load_dwordx4 v[184:187], v[130:131], off offset:576
	v_lshl_add_u64 v[144:145], v[196:197], 0, s[10:11]
	v_lshl_add_u64 v[146:147], v[196:197], 0, s[10:11]
	v_mov_b32_e32 v188, 0
	v_mov_b32_e32 v189, 0
	v_mov_b32_e32 v190, 0
	v_mov_b32_e32 v191, 0
	v_mov_b32_e32 v192, 0
	v_mov_b32_e32 v193, 0
	v_mov_b32_e32 v194, 0
	v_mov_b32_e32 v195, 0
	global_load_dwordx4 v[208:211], v[144:145], off
	global_load_dwordx4 v[212:215], v[144:145], off offset:64
	global_load_dwordx4 v[216:219], v[144:145], off offset:512
	global_load_dwordx4 v[220:223], v[144:145], off offset:576
	v_lshl_add_u64 v[144:145], v[144:145], 0, s[66:67]
	global_load_dwordx4 v[224:227], v[144:145], off
	global_load_dwordx4 v[228:231], v[144:145], off offset:64
	global_load_dwordx4 v[232:235], v[144:145], off offset:512
	global_load_dwordx4 v[236:239], v[144:145], off offset:576
	v_lshl_add_u64 v[144:145], v[144:145], 0, s[66:67]
	s_waitcnt vmcnt(4)
	v_pk_mul_f32 v[126:127], v[126:127], v[242:243]
	v_pk_mul_f32 v[124:125], v[124:125], v[240:241]
	v_pk_add_f32 v[126:127], v[126:127], v[210:211]
	v_pk_add_f32 v[124:125], v[124:125], v[208:209]
	v_pk_mul_f32 v[122:123], v[122:123], v[246:247]
	v_pk_mul_f32 v[120:121], v[120:121], v[244:245]
	v_pk_add_f32 v[122:123], v[122:123], v[214:215]
	v_pk_add_f32 v[120:121], v[120:121], v[212:213]
	v_pk_mul_f32 v[118:119], v[118:119], v[250:251]
	v_pk_mul_f32 v[116:117], v[116:117], v[248:249]
	v_pk_add_f32 v[118:119], v[118:119], v[218:219]
	v_pk_add_f32 v[116:117], v[116:117], v[216:217]
	v_pk_mul_f32 v[114:115], v[114:115], v[186:187]
	v_pk_mul_f32 v[112:113], v[112:113], v[184:185]
	v_pk_add_f32 v[114:115], v[114:115], v[222:223]
	v_pk_add_f32 v[112:113], v[112:113], v[220:221]
	v_pk_mul_f32 v[140:141], v[124:125], v[124:125]
	v_pk_fma_f32 v[140:141], v[126:127], v[126:127], v[140:141]
	v_add_f32_e32 v188, v188, v140
	v_add_f32_e32 v188, v188, v141
	v_pk_mul_f32 v[140:141], v[120:121], v[120:121]
	v_pk_fma_f32 v[140:141], v[122:123], v[122:123], v[140:141]
	v_add_f32_e32 v188, v188, v140
	v_add_f32_e32 v188, v188, v141
	v_pk_mul_f32 v[140:141], v[116:117], v[116:117]
	v_pk_fma_f32 v[140:141], v[118:119], v[118:119], v[140:141]
	v_add_f32_e32 v188, v188, v140
	v_add_f32_e32 v188, v188, v141
	v_pk_mul_f32 v[140:141], v[112:113], v[112:113]
	v_pk_fma_f32 v[140:141], v[114:115], v[114:115], v[140:141]
	v_add_f32_e32 v188, v188, v140
	v_add_f32_e32 v188, v188, v141
	global_load_dwordx4 v[208:211], v[144:145], off
	global_load_dwordx4 v[212:215], v[144:145], off offset:64
	global_load_dwordx4 v[216:219], v[144:145], off offset:512
	global_load_dwordx4 v[220:223], v[144:145], off offset:576
	v_lshl_add_u64 v[144:145], v[144:145], 0, s[66:67]
	s_waitcnt vmcnt(4)
	v_pk_mul_f32 v[110:111], v[110:111], v[242:243]
	v_pk_mul_f32 v[108:109], v[108:109], v[240:241]
	v_pk_add_f32 v[110:111], v[110:111], v[226:227]
	v_pk_add_f32 v[108:109], v[108:109], v[224:225]
	v_pk_mul_f32 v[106:107], v[106:107], v[246:247]
	v_pk_mul_f32 v[104:105], v[104:105], v[244:245]
	v_pk_add_f32 v[106:107], v[106:107], v[230:231]
	v_pk_add_f32 v[104:105], v[104:105], v[228:229]
	v_pk_mul_f32 v[102:103], v[102:103], v[250:251]
	v_pk_mul_f32 v[100:101], v[100:101], v[248:249]
	v_pk_add_f32 v[102:103], v[102:103], v[234:235]
	v_pk_add_f32 v[100:101], v[100:101], v[232:233]
	v_pk_mul_f32 v[98:99], v[98:99], v[186:187]
	v_pk_mul_f32 v[96:97], v[96:97], v[184:185]
	v_pk_add_f32 v[98:99], v[98:99], v[238:239]
	v_pk_add_f32 v[96:97], v[96:97], v[236:237]
	v_pk_mul_f32 v[140:141], v[108:109], v[108:109]
	v_pk_fma_f32 v[140:141], v[110:111], v[110:111], v[140:141]
	v_add_f32_e32 v189, v189, v140
	v_add_f32_e32 v189, v189, v141
	v_pk_mul_f32 v[140:141], v[104:105], v[104:105]
	v_pk_fma_f32 v[140:141], v[106:107], v[106:107], v[140:141]
	v_add_f32_e32 v189, v189, v140
	v_add_f32_e32 v189, v189, v141
	v_pk_mul_f32 v[140:141], v[100:101], v[100:101]
	v_pk_fma_f32 v[140:141], v[102:103], v[102:103], v[140:141]
	v_add_f32_e32 v189, v189, v140
	v_add_f32_e32 v189, v189, v141
	v_pk_mul_f32 v[140:141], v[96:97], v[96:97]
	v_pk_fma_f32 v[140:141], v[98:99], v[98:99], v[140:141]
	v_add_f32_e32 v189, v189, v140
	v_add_f32_e32 v189, v189, v141
	global_load_dwordx4 v[224:227], v[144:145], off
	global_load_dwordx4 v[228:231], v[144:145], off offset:64
	global_load_dwordx4 v[232:235], v[144:145], off offset:512
	global_load_dwordx4 v[236:239], v[144:145], off offset:576
	v_lshl_add_u64 v[144:145], v[144:145], 0, s[68:69]
	s_waitcnt vmcnt(4)
;     __device__ __forceinline__ void operator()(const Acc& acc, const Unit& u, int wr, int wc, int fr, int fq) const {
;     ...
;             for (int m = 0; m < 4; ++m) { const int row = u.pm * 256 + ai * 128 + wr * 64 + m * 16 + fr;
;                 const float* base = xp ? (row < MP ? xp + (size_t)row * D : xs + (size_t)(row - MP) * D) : X + (size_t)row * D;
;                 const float* gp = gate + (size_t)mod_row(row) * 6144;
; #pragma unroll
;                 for (int bj = 0; bj < 2; ++bj)
; #pragma unroll
;                     for (int n = 0; n < 2; ++n) { const int col = u.pn * 256 + bj * 128 + wc * 32 + n * 16 + fq * 4;
;                         const f32x4 ga = *(const f32x4*)(gp + col) * acc[ai][bj][m][n];
;                         if (u.split) { *(f32x4*)(part + ((size_t)(u.k0 >> 8) * MS + (row - MP)) * D + col) = ga;
;                         } else *(f32x4*)(X + (size_t)row * D + col) = *(const f32x4*)(base + col) + ga; } }
; template <bool FINAL>
; __device__ __forceinline__ void norm_rows(const float* xp, const float* xs, const float* X, const float* g, const float* sh, const float* sc, bf16_t* XN, float* out, int gw, int NGW, int lane, const float* part, int nsplit) {
;     ...
;         for (int j = 0; j < 4; ++j) s += (v[j][0] * v[j][0] + v[j][1] * v[j][1]) + (v[j][2] * v[j][2] + v[j][3] * v[j][3]);
	v_pk_mul_f32 v[94:95], v[94:95], v[242:243]
	v_pk_mul_f32 v[92:93], v[92:93], v[240:241]
	v_pk_add_f32 v[94:95], v[94:95], v[210:211]
	v_pk_add_f32 v[92:93], v[92:93], v[208:209]
	v_pk_mul_f32 v[90:91], v[90:91], v[246:247]
	v_pk_mul_f32 v[88:89], v[88:89], v[244:245]
	v_pk_add_f32 v[90:91], v[90:91], v[214:215]
	v_pk_add_f32 v[88:89], v[88:89], v[212:213]
	v_pk_mul_f32 v[86:87], v[86:87], v[250:251]
	v_pk_mul_f32 v[84:85], v[84:85], v[248:249]
	v_pk_add_f32 v[86:87], v[86:87], v[218:219]
	v_pk_add_f32 v[84:85], v[84:85], v[216:217]
	v_pk_mul_f32 v[82:83], v[82:83], v[186:187]
	v_pk_mul_f32 v[80:81], v[80:81], v[184:185]
	v_pk_add_f32 v[82:83], v[82:83], v[222:223]
	v_pk_add_f32 v[80:81], v[80:81], v[220:221]
	v_pk_mul_f32 v[140:141], v[92:93], v[92:93]
	v_pk_fma_f32 v[140:141], v[94:95], v[94:95], v[140:141]
	v_add_f32_e32 v190, v190, v140
	v_add_f32_e32 v190, v190, v141
	v_pk_mul_f32 v[140:141], v[88:89], v[88:89]
	v_pk_fma_f32 v[140:141], v[90:91], v[90:91], v[140:141]
	v_add_f32_e32 v190, v190, v140
	v_add_f32_e32 v190, v190, v141
	v_pk_mul_f32 v[140:141], v[84:85], v[84:85]
	v_pk_fma_f32 v[140:141], v[86:87], v[86:87], v[140:141]
	v_add_f32_e32 v190, v190, v140
	v_add_f32_e32 v190, v190, v141
	v_pk_mul_f32 v[140:141], v[80:81], v[80:81]
	v_pk_fma_f32 v[140:141], v[82:83], v[82:83], v[140:141]
	v_add_f32_e32 v190, v190, v140
	v_add_f32_e32 v190, v190, v141
	global_load_dwordx4 v[208:211], v[144:145], off
	global_load_dwordx4 v[212:215], v[144:145], off offset:64
	global_load_dwordx4 v[216:219], v[144:145], off offset:512
	global_load_dwordx4 v[220:223], v[144:145], off offset:576
	v_lshl_add_u64 v[144:145], v[144:145], 0, s[66:67]
	s_waitcnt vmcnt(4)
	v_pk_mul_f32 v[78:79], v[78:79], v[242:243]
	v_pk_mul_f32 v[76:77], v[76:77], v[240:241]
	v_pk_add_f32 v[78:79], v[78:79], v[226:227]
	v_pk_add_f32 v[76:77], v[76:77], v[224:225]
	v_pk_mul_f32 v[74:75], v[74:75], v[246:247]
	v_pk_mul_f32 v[72:73], v[72:73], v[244:245]
	v_pk_add_f32 v[74:75], v[74:75], v[230:231]
	v_pk_add_f32 v[72:73], v[72:73], v[228:229]
	v_pk_mul_f32 v[70:71], v[70:71], v[250:251]
	v_pk_mul_f32 v[68:69], v[68:69], v[248:249]
	v_pk_add_f32 v[70:71], v[70:71], v[234:235]
	v_pk_add_f32 v[68:69], v[68:69], v[232:233]
	v_pk_mul_f32 v[66:67], v[66:67], v[186:187]
	v_pk_mul_f32 v[64:65], v[64:65], v[184:185]
	v_pk_add_f32 v[66:67], v[66:67], v[238:239]
	v_pk_add_f32 v[64:65], v[64:65], v[236:237]
	v_pk_mul_f32 v[140:141], v[76:77], v[76:77]
	v_pk_fma_f32 v[140:141], v[78:79], v[78:79], v[140:141]
	v_add_f32_e32 v191, v191, v140
	v_add_f32_e32 v191, v191, v141
	v_pk_mul_f32 v[140:141], v[72:73], v[72:73]
	v_pk_fma_f32 v[140:141], v[74:75], v[74:75], v[140:141]
	v_add_f32_e32 v191, v191, v140
	v_add_f32_e32 v191, v191, v141
	v_pk_mul_f32 v[140:141], v[68:69], v[68:69]
	v_pk_fma_f32 v[140:141], v[70:71], v[70:71], v[140:141]
	v_add_f32_e32 v191, v191, v140
	v_add_f32_e32 v191, v191, v141
	v_pk_mul_f32 v[140:141], v[64:65], v[64:65]
	v_pk_fma_f32 v[140:141], v[66:67], v[66:67], v[140:141]
	v_add_f32_e32 v191, v191, v140
	v_add_f32_e32 v191, v191, v141
	global_load_dwordx4 v[224:227], v[144:145], off
	global_load_dwordx4 v[228:231], v[144:145], off offset:64
	global_load_dwordx4 v[232:235], v[144:145], off offset:512
	global_load_dwordx4 v[236:239], v[144:145], off offset:576
	v_lshl_add_u64 v[144:145], v[144:145], 0, s[66:67]
	s_waitcnt vmcnt(4)
	v_pk_mul_f32 v[62:63], v[62:63], v[242:243]
	v_pk_mul_f32 v[60:61], v[60:61], v[240:241]
	v_pk_add_f32 v[62:63], v[62:63], v[210:211]
	v_pk_add_f32 v[60:61], v[60:61], v[208:209]
	v_pk_mul_f32 v[58:59], v[58:59], v[246:247]
	v_pk_mul_f32 v[56:57], v[56:57], v[244:245]
	v_pk_add_f32 v[58:59], v[58:59], v[214:215]
	v_pk_add_f32 v[56:57], v[56:57], v[212:213]
	v_pk_mul_f32 v[54:55], v[54:55], v[250:251]
	v_pk_mul_f32 v[52:53], v[52:53], v[248:249]
	v_pk_add_f32 v[54:55], v[54:55], v[218:219]
	v_pk_add_f32 v[52:53], v[52:53], v[216:217]
	v_pk_mul_f32 v[50:51], v[50:51], v[186:187]
	v_pk_mul_f32 v[48:49], v[48:49], v[184:185]
	v_pk_add_f32 v[50:51], v[50:51], v[222:223]
	v_pk_add_f32 v[48:49], v[48:49], v[220:221]
	v_pk_mul_f32 v[140:141], v[60:61], v[60:61]
	v_pk_fma_f32 v[140:141], v[62:63], v[62:63], v[140:141]
	v_add_f32_e32 v192, v192, v140
	v_add_f32_e32 v192, v192, v141
	v_pk_mul_f32 v[140:141], v[56:57], v[56:57]
	v_pk_fma_f32 v[140:141], v[58:59], v[58:59], v[140:141]
	v_add_f32_e32 v192, v192, v140
	v_add_f32_e32 v192, v192, v141
	v_pk_mul_f32 v[140:141], v[52:53], v[52:53]
	v_pk_fma_f32 v[140:141], v[54:55], v[54:55], v[140:141]
	v_add_f32_e32 v192, v192, v140
	v_add_f32_e32 v192, v192, v141
	v_pk_mul_f32 v[140:141], v[48:49], v[48:49]
	v_pk_fma_f32 v[140:141], v[50:51], v[50:51], v[140:141]
	v_add_f32_e32 v192, v192, v140
	v_add_f32_e32 v192, v192, v141
	global_load_dwordx4 v[208:211], v[144:145], off
	global_load_dwordx4 v[212:215], v[144:145], off offset:64
	global_load_dwordx4 v[216:219], v[144:145], off offset:512
	global_load_dwordx4 v[220:223], v[144:145], off offset:576
	v_lshl_add_u64 v[144:145], v[144:145], 0, s[66:67]
	s_waitcnt vmcnt(4)
;     __device__ __forceinline__ void operator()(const Acc& acc, const Unit& u, int wr, int wc, int fr, int fq) const {
;     ...
;             for (int m = 0; m < 4; ++m) { const int row = u.pm * 256 + ai * 128 + wr * 64 + m * 16 + fr;
;                 const float* base = xp ? (row < MP ? xp + (size_t)row * D : xs + (size_t)(row - MP) * D) : X + (size_t)row * D;
;                 const float* gp = gate + (size_t)mod_row(row) * 6144;
; #pragma unroll
;                 for (int bj = 0; bj < 2; ++bj)
; #pragma unroll
;                     for (int n = 0; n < 2; ++n) { const int col = u.pn * 256 + bj * 128 + wc * 32 + n * 16 + fq * 4;
;                         const f32x4 ga = *(const f32x4*)(gp + col) * acc[ai][bj][m][n];
;                         if (u.split) { *(f32x4*)(part + ((size_t)(u.k0 >> 8) * MS + (row - MP)) * D + col) = ga;
;                         } else *(f32x4*)(X + (size_t)row * D + col) = *(const f32x4*)(base + col) + ga; } }
; template <bool FINAL>
; __device__ __forceinline__ void norm_rows(const float* xp, const float* xs, const float* X, const float* g, const float* sh, const float* sc, bf16_t* XN, float* out, int gw, int NGW, int lane, const float* part, int nsplit) {
;     ...
;         for (int j = 0; j < 4; ++j) s += (v[j][0] * v[j][0] + v[j][1] * v[j][1]) + (v[j][2] * v[j][2] + v[j][3] * v[j][3]);
;         const float rstd = 1.0f / sqrtf(wave_sum(s) * (1.0f / D) + EPS);
	v_pk_mul_f32 v[46:47], v[46:47], v[242:243]
	v_pk_mul_f32 v[44:45], v[44:45], v[240:241]
	v_pk_add_f32 v[46:47], v[46:47], v[226:227]
	v_pk_add_f32 v[44:45], v[44:45], v[224:225]
	v_pk_mul_f32 v[42:43], v[42:43], v[246:247]
	v_pk_mul_f32 v[40:41], v[40:41], v[244:245]
	v_pk_add_f32 v[42:43], v[42:43], v[230:231]
	v_pk_add_f32 v[40:41], v[40:41], v[228:229]
	v_pk_mul_f32 v[38:39], v[38:39], v[250:251]
	v_pk_mul_f32 v[36:37], v[36:37], v[248:249]
	v_pk_add_f32 v[38:39], v[38:39], v[234:235]
	v_pk_add_f32 v[36:37], v[36:37], v[232:233]
	v_pk_mul_f32 v[34:35], v[34:35], v[186:187]
	v_pk_mul_f32 v[32:33], v[32:33], v[184:185]
	v_pk_add_f32 v[34:35], v[34:35], v[238:239]
	v_pk_add_f32 v[32:33], v[32:33], v[236:237]
	v_pk_mul_f32 v[140:141], v[44:45], v[44:45]
	v_pk_fma_f32 v[140:141], v[46:47], v[46:47], v[140:141]
	v_add_f32_e32 v193, v193, v140
	v_add_f32_e32 v193, v193, v141
	v_pk_mul_f32 v[140:141], v[40:41], v[40:41]
	v_pk_fma_f32 v[140:141], v[42:43], v[42:43], v[140:141]
	v_add_f32_e32 v193, v193, v140
	v_add_f32_e32 v193, v193, v141
	v_pk_mul_f32 v[140:141], v[36:37], v[36:37]
	v_pk_fma_f32 v[140:141], v[38:39], v[38:39], v[140:141]
	v_add_f32_e32 v193, v193, v140
	v_add_f32_e32 v193, v193, v141
	v_pk_mul_f32 v[140:141], v[32:33], v[32:33]
	v_pk_fma_f32 v[140:141], v[34:35], v[34:35], v[140:141]
	v_add_f32_e32 v193, v193, v140
	v_add_f32_e32 v193, v193, v141
	global_load_dwordx4 v[224:227], v[144:145], off
	global_load_dwordx4 v[228:231], v[144:145], off offset:64
	global_load_dwordx4 v[232:235], v[144:145], off offset:512
	global_load_dwordx4 v[236:239], v[144:145], off offset:576
	s_waitcnt vmcnt(4)
	v_pk_mul_f32 v[30:31], v[30:31], v[242:243]
	v_pk_mul_f32 v[28:29], v[28:29], v[240:241]
	v_pk_add_f32 v[30:31], v[30:31], v[210:211]
	v_pk_add_f32 v[28:29], v[28:29], v[208:209]
	v_pk_mul_f32 v[26:27], v[26:27], v[246:247]
	v_pk_mul_f32 v[24:25], v[24:25], v[244:245]
	v_pk_add_f32 v[26:27], v[26:27], v[214:215]
	v_pk_add_f32 v[24:25], v[24:25], v[212:213]
	v_pk_mul_f32 v[22:23], v[22:23], v[250:251]
	v_pk_mul_f32 v[20:21], v[20:21], v[248:249]
	v_pk_add_f32 v[22:23], v[22:23], v[218:219]
	v_pk_add_f32 v[20:21], v[20:21], v[216:217]
	v_pk_mul_f32 v[18:19], v[18:19], v[186:187]
	v_pk_mul_f32 v[16:17], v[16:17], v[184:185]
	v_pk_add_f32 v[18:19], v[18:19], v[222:223]
	v_pk_add_f32 v[16:17], v[16:17], v[220:221]
	v_pk_mul_f32 v[140:141], v[28:29], v[28:29]
	v_pk_fma_f32 v[140:141], v[30:31], v[30:31], v[140:141]
	v_add_f32_e32 v194, v194, v140
	v_add_f32_e32 v194, v194, v141
	v_pk_mul_f32 v[140:141], v[24:25], v[24:25]
	v_pk_fma_f32 v[140:141], v[26:27], v[26:27], v[140:141]
	v_add_f32_e32 v194, v194, v140
	v_add_f32_e32 v194, v194, v141
	v_pk_mul_f32 v[140:141], v[20:21], v[20:21]
	v_pk_fma_f32 v[140:141], v[22:23], v[22:23], v[140:141]
	v_add_f32_e32 v194, v194, v140
	v_add_f32_e32 v194, v194, v141
	v_pk_mul_f32 v[140:141], v[16:17], v[16:17]
	v_pk_fma_f32 v[140:141], v[18:19], v[18:19], v[140:141]
	v_add_f32_e32 v194, v194, v140
	v_add_f32_e32 v194, v194, v141
	s_waitcnt vmcnt(0)
	v_pk_mul_f32 v[14:15], v[14:15], v[242:243]
	v_pk_mul_f32 v[12:13], v[12:13], v[240:241]
	v_pk_add_f32 v[14:15], v[14:15], v[226:227]
	v_pk_add_f32 v[12:13], v[12:13], v[224:225]
	v_pk_mul_f32 v[10:11], v[10:11], v[246:247]
	v_pk_mul_f32 v[8:9], v[8:9], v[244:245]
	v_pk_add_f32 v[10:11], v[10:11], v[230:231]
	v_pk_add_f32 v[8:9], v[8:9], v[228:229]
	v_pk_mul_f32 v[6:7], v[6:7], v[250:251]
	v_pk_mul_f32 v[4:5], v[4:5], v[248:249]
	v_pk_add_f32 v[6:7], v[6:7], v[234:235]
	v_pk_add_f32 v[4:5], v[4:5], v[232:233]
	v_pk_mul_f32 v[2:3], v[2:3], v[186:187]
	v_pk_mul_f32 v[0:1], v[0:1], v[184:185]
	v_pk_add_f32 v[2:3], v[2:3], v[238:239]
	v_pk_add_f32 v[0:1], v[0:1], v[236:237]
	v_pk_mul_f32 v[140:141], v[12:13], v[12:13]
	v_pk_fma_f32 v[140:141], v[14:15], v[14:15], v[140:141]
	v_add_f32_e32 v195, v195, v140
	v_add_f32_e32 v195, v195, v141
	v_pk_mul_f32 v[140:141], v[8:9], v[8:9]
	v_pk_fma_f32 v[140:141], v[10:11], v[10:11], v[140:141]
	v_add_f32_e32 v195, v195, v140
	v_add_f32_e32 v195, v195, v141
	v_pk_mul_f32 v[140:141], v[4:5], v[4:5]
	v_pk_fma_f32 v[140:141], v[6:7], v[6:7], v[140:141]
	v_add_f32_e32 v195, v195, v140
	v_add_f32_e32 v195, v195, v141
	v_pk_mul_f32 v[140:141], v[0:1], v[0:1]
	v_pk_fma_f32 v[140:141], v[2:3], v[2:3], v[140:141]
	v_add_f32_e32 v195, v195, v140
	v_add_f32_e32 v195, v195, v141
	ds_swizzle_b32 v208, v188 offset:swizzle(SWAP,16)
	ds_swizzle_b32 v209, v189 offset:swizzle(SWAP,16)
	ds_swizzle_b32 v210, v190 offset:swizzle(SWAP,16)
	ds_swizzle_b32 v211, v191 offset:swizzle(SWAP,16)
	ds_swizzle_b32 v212, v192 offset:swizzle(SWAP,16)
	ds_swizzle_b32 v213, v193 offset:swizzle(SWAP,16)
	ds_swizzle_b32 v214, v194 offset:swizzle(SWAP,16)
	ds_swizzle_b32 v215, v195 offset:swizzle(SWAP,16)
	s_waitcnt lgkmcnt(0)
	v_add_f32_e32 v188, v188, v208
	v_add_f32_e32 v189, v189, v209
	v_add_f32_e32 v190, v190, v210
	v_add_f32_e32 v191, v191, v211
	v_add_f32_e32 v192, v192, v212
	v_add_f32_e32 v193, v193, v213
	v_add_f32_e32 v194, v194, v214
	v_add_f32_e32 v195, v195, v215
	v_mov_b32_e32 v208, v188
	v_mov_b32_e32 v209, v189
	v_mov_b32_e32 v210, v190
	v_mov_b32_e32 v211, v191
	v_mov_b32_e32 v212, v192
	v_mov_b32_e32 v213, v193
	v_mov_b32_e32 v214, v194
	v_mov_b32_e32 v215, v195
	s_nop 1
	v_permlane32_swap_b32 v188, v208
	v_permlane32_swap_b32 v189, v209
	v_permlane32_swap_b32 v190, v210
	v_permlane32_swap_b32 v191, v211
	v_permlane32_swap_b32 v192, v212
	v_permlane32_swap_b32 v193, v213
	v_permlane32_swap_b32 v194, v214
	v_permlane32_swap_b32 v195, v215
	s_nop 1
	v_add_f32_e32 v188, v188, v208
	v_add_f32_e32 v189, v189, v209
	v_add_f32_e32 v190, v190, v210
	v_add_f32_e32 v191, v191, v211
	v_add_f32_e32 v192, v192, v212
	v_add_f32_e32 v193, v193, v213
	v_add_f32_e32 v194, v194, v214
	v_add_f32_e32 v195, v195, v215
	v_readlane_b32 s25, v253, 2
	s_nop 3
	s_and_b32 s27, s25, 3
	s_lshl_b32 s27, s27, 10
	s_add_i32 s27, s27, 0x20800
	v_lshl_add_u32 v143, v142, 2, s27
	ds_write_b32 v143, v188
	ds_write_b32 v143, v189 offset:64
	ds_write_b32 v143, v190 offset:128
	ds_write_b32 v143, v191 offset:192
	ds_write_b32 v143, v192 offset:512
	ds_write_b32 v143, v193 offset:576
	ds_write_b32 v143, v194 offset:640
	ds_write_b32 v143, v195 offset:704
	v_mbcnt_lo_u32_b32 v207, -1, 0
	v_mbcnt_hi_u32_b32 v207, -1, v207
	s_lshl_b32 s27, s25, 6
	v_add_u32_e32 v207, s27, v207
	v_lshlrev_b32_e32 v207, 2, v207
	s_sub_u32 s70, s10, 0x7800000
	s_subb_u32 s71, s11, 0
	s_lshl_b32 s74, s55, 11
	s_add_u32 s70, s70, s74
	s_addc_u32 s71, s71, 0
	s_lshl_b32 s32, s96, 3
	s_add_i32 s32, s32, 8
	s_or_b32 s32, s32, 0xc0de0000
	s_waitcnt lgkmcnt(0)
	s_barrier
; #define INP(i) ((const float*)ld_ptr(pb, (i)))
;     __device__ __forceinline__ void operator()(const Acc& acc, const Unit& u, int wr, int wc, int fr, int fq) const {
;     ...
;                         } else *(f32x4*)(X + (size_t)row * D + col) = *(const f32x4*)(base + col) + ga; } }
; template <bool FINAL>
; __device__ __forceinline__ void norm_rows(const float* xp, const float* xs, const float* X, const float* g, const float* sh, const float* sc, bf16_t* XN, float* out, int gw, int NGW, int lane, const float* part, int nsplit) {
;     ...
;         const float rstd = 1.0f / sqrtf(wave_sum(s) * (1.0f / D) + EPS);
;         const int mr = mod_row(row);
;         if (!FINAL && xp && row >= MP) {
; #pragma unroll
;             for (int j = 0; j < 4; ++j) *(f32x4*)((float*)X + (size_t)row * D + 4 * lane + 256 * j) = v[j]; }
; #pragma unroll
;         for (int j = 0; j < 4; ++j) { const int col = 4 * lane + 256 * j; const f32x4 gg = *(const f32x4*)(g + col);
;             if (FINAL) { *(f32x4*)(out + (size_t)row * D + col) = v[j] * rstd * gg; }
;             else { const f32x4 s1 = *(const f32x4*)(sc + (size_t)mr * 6144 + col), s0 = *(const f32x4*)(sh + (size_t)mr * 6144 + col);
; __global__ void __launch_bounds__(512, 2) hybrid_fwd(Params P) {
;     ...
;         if (l + 1 < DEPTH) norm_rows<false>(nullptr, nullptr, X, INP(9) + (l + 1) * D, (MOD + (size_t)l * NMODROWS * 6144) + (size_t)NMODROWS * 6144, (MOD + (size_t)l * NMODROWS * 6144) + (size_t)NMODROWS * 6144 + 1024, XN, nullptr, gw, NGW, lane, (const float*)(ws + WS_PART), DFF / 256);
	s_cmp_lt_u32 s25, 4
	s_cbranch_scc0 .Lfz_dn_nopub
	v_add_u32_e32 v140, 0x20800, v207
	ds_read_b32 v212, v140
	ds_read_b32 v213, v140 offset:1024
	ds_read_b32 v214, v140 offset:2048
	ds_read_b32 v215, v140 offset:3072
	v_lshlrev_b32_e32 v188, 1, v207
	s_lshl_b32 s74, s53, 17
	v_add_u32_e32 v141, s74, v188
	s_waitcnt lgkmcnt(0)
	v_add_f32_e32 v212, v212, v213
	v_add_f32_e32 v212, v212, v214
	v_add_f32_e32 v212, v212, v215
	v_mov_b32_e32 v213, s32
	global_store_dwordx2 v141, v[212:213], s[70:71] sc0 sc1
.Lfz_dn_nopub:
	v_mov_b32_e32 v140, 0x20448
	ds_read_b64 v[140:141], v140
	s_waitcnt lgkmcnt(0)
	v_readfirstlane_b32 s2, v140
	v_readfirstlane_b32 s3, v141
	s_add_i32 s74, s96, 1
	s_lshl_b32 s74, s74, 12
	s_add_u32 s2, s2, s74
	s_addc_u32 s3, s3, 0
	s_nop 4
	global_load_dwordx4 v[208:211], v159, s[2:3]
	global_load_dwordx4 v[212:215], v159, s[2:3] offset:64
	global_load_dwordx4 v[216:219], v159, s[2:3] offset:512
	global_load_dwordx4 v[220:223], v159, s[2:3] offset:576
	s_mov_b32 s74, 0x313000
	v_add_co_u32_e32 v130, vcc, s74, v130
	s_nop 1
	v_addc_co_u32_e32 v131, vcc, 0, v131, vcc
	global_load_dwordx4 v[240:243], v[130:131], off
	global_load_dwordx4 v[244:247], v[130:131], off offset:64
	global_load_dwordx4 v[248:251], v[130:131], off offset:512
	global_load_dwordx4 v[184:187], v[130:131], off offset:576
	v_add_co_u32_e32 v130, vcc, 0x1000, v130
	s_nop 1
	v_addc_co_u32_e32 v131, vcc, 0, v131, vcc
	global_load_dwordx4 v[224:227], v[130:131], off
	global_load_dwordx4 v[228:231], v[130:131], off offset:64
	global_load_dwordx4 v[232:235], v[130:131], off offset:512
	global_load_dwordx4 v[236:239], v[130:131], off offset:576
	global_store_dwordx4 v[146:147], v[124:127], off
	global_store_dwordx4 v[146:147], v[120:123], off offset:64
	global_store_dwordx4 v[146:147], v[116:119], off offset:512
	global_store_dwordx4 v[146:147], v[112:115], off offset:576
	v_lshl_add_u64 v[146:147], v[146:147], 0, s[66:67]
	global_store_dwordx4 v[146:147], v[108:111], off
	global_store_dwordx4 v[146:147], v[104:107], off offset:64
	global_store_dwordx4 v[146:147], v[100:103], off offset:512
	global_store_dwordx4 v[146:147], v[96:99], off offset:576
	v_lshl_add_u64 v[146:147], v[146:147], 0, s[66:67]
	global_store_dwordx4 v[146:147], v[92:95], off
	global_store_dwordx4 v[146:147], v[88:91], off offset:64
	global_store_dwordx4 v[146:147], v[84:87], off offset:512
	global_store_dwordx4 v[146:147], v[80:83], off offset:576
	v_lshl_add_u64 v[146:147], v[146:147], 0, s[66:67]
	global_store_dwordx4 v[146:147], v[76:79], off
	global_store_dwordx4 v[146:147], v[72:75], off offset:64
	global_store_dwordx4 v[146:147], v[68:71], off offset:512
	global_store_dwordx4 v[146:147], v[64:67], off offset:576
	v_lshl_add_u64 v[146:147], v[146:147], 0, s[68:69]
	global_store_dwordx4 v[146:147], v[60:63], off
	global_store_dwordx4 v[146:147], v[56:59], off offset:64
	global_store_dwordx4 v[146:147], v[52:55], off offset:512
	global_store_dwordx4 v[146:147], v[48:51], off offset:576
	v_lshl_add_u64 v[146:147], v[146:147], 0, s[66:67]
	global_store_dwordx4 v[146:147], v[44:47], off
	global_store_dwordx4 v[146:147], v[40:43], off offset:64
	global_store_dwordx4 v[146:147], v[36:39], off offset:512
	global_store_dwordx4 v[146:147], v[32:35], off offset:576
	v_lshl_add_u64 v[146:147], v[146:147], 0, s[66:67]
	global_store_dwordx4 v[146:147], v[28:31], off
	global_store_dwordx4 v[146:147], v[24:27], off offset:64
	global_store_dwordx4 v[146:147], v[20:23], off offset:512
	global_store_dwordx4 v[146:147], v[16:19], off offset:576
	v_lshl_add_u64 v[146:147], v[146:147], 0, s[66:67]
	global_store_dwordx4 v[146:147], v[12:15], off
	global_store_dwordx4 v[146:147], v[8:11], off offset:64
	global_store_dwordx4 v[146:147], v[4:7], off offset:512
	global_store_dwordx4 v[146:147], v[0:3], off offset:576
	s_cmp_lt_u32 s25, 4
	s_cbranch_scc0 .Lfz_dn_norstd
	v_add_u32_e32 v189, 0x20000, v188
	v_add_u32_e32 v190, 0x40000, v188
	v_add_u32_e32 v191, 0x60000, v188
	s_mov_b32 s65, 0

; #define INP(i) ((const float*)ld_ptr(pb, (i)))
;     __device__ __forceinline__ void operator()(const Acc& acc, const Unit& u, int wr, int wc, int fr, int fq) const {
; #pragma unroll
;         for (int ai = 0; ai < 2; ++ai)
; #pragma unroll
;             for (int m = 0; m < 4; ++m) { const int row = u.pm * 256 + ai * 128 + wr * 64 + m * 16 + fr;
;                 const float* base = xp ? (row < MP ? xp + (size_t)row * D : xs + (size_t)(row - MP) * D) : X + (size_t)row * D;
;                 const float* gp = gate + (size_t)mod_row(row) * 6144;
; #pragma unroll
;                 for (int bj = 0; bj < 2; ++bj)
; #pragma unroll
;                     for (int n = 0; n < 2; ++n) { const int col = u.pn * 256 + bj * 128 + wc * 32 + n * 16 + fq * 4;
;                         const f32x4 ga = *(const f32x4*)(gp + col) * acc[ai][bj][m][n];
;                         if (u.split) { *(f32x4*)(part + ((size_t)(u.k0 >> 8) * MS + (row - MP)) * D + col) = ga;
;                         } else *(f32x4*)(X + (size_t)row * D + col) = *(const f32x4*)(base + col) + ga; } }
; __global__ void __launch_bounds__(512, 2) hybrid_fwd(Params P) {
;     ...
;         else norm_rows<true>(nullptr, nullptr, X, INP(33), nullptr, nullptr, nullptr, out, gw, NGW, lane, (const float*)(ws + WS_PART), DFF / 256);
.Lepi_dn_final:
	s_mov_b32 s66, 0x10000
	s_mov_b32 s67, 0
	s_mov_b32 s68, 0x50000
	s_mov_b32 s69, 0
	v_lshlrev_b32_e32 v140, 11, v207
	v_lshl_add_u32 v140, v159, 1, v140
	v_mov_b32_e32 v141, 0
	s_add_u32 s70, s10, 0x4200000
	s_addc_u32 s71, s11, 0
	v_lshl_add_u64 v[128:129], v[140:141], 0, s[70:71]
	v_lshlrev_b32_e32 v196, 12, v207
	v_lshl_add_u32 v196, v159, 2, v196
	v_add_u32_e32 v142, s43, v151
	v_lshrrev_b32_e32 v207, 12, v207
	v_lshlrev_b32_e32 v159, 2, v159
	v_mad_u32_u24 v130, v207, s80, v159
	v_mov_b32_e32 v131, 0
	v_lshl_add_u64 v[130:131], v[130:131], 0, s[12:13]
	global_load_dwordx4 v[240:243], v[130:131], off
	global_load_dwordx4 v[244:247], v[130:131], off offset:64
	global_load_dwordx4 v[248:251], v[130:131], off offset:512
	global_load_dwordx4 v[184:187], v[130:131], off offset:576
	v_mov_b32_e32 v140, 0x20510
	ds_read_b64 v[140:141], v140
	v_lshl_add_u64 v[144:145], v[196:197], 0, s[10:11]
	s_waitcnt lgkmcnt(0)
	v_readfirstlane_b32 s2, v140
	v_readfirstlane_b32 s3, v141
	s_nop 3
	v_lshl_add_u64 v[146:147], v[196:197], 0, s[2:3]
	v_mov_b32_e32 v188, 0
	v_mov_b32_e32 v189, 0
	v_mov_b32_e32 v190, 0
	v_mov_b32_e32 v191, 0
	v_mov_b32_e32 v192, 0
	v_mov_b32_e32 v193, 0
	v_mov_b32_e32 v194, 0
	v_mov_b32_e32 v195, 0
	global_load_dwordx4 v[208:211], v[144:145], off
	global_load_dwordx4 v[212:215], v[144:145], off offset:64
	global_load_dwordx4 v[216:219], v[144:145], off offset:512
	global_load_dwordx4 v[220:223], v[144:145], off offset:576
	v_lshl_add_u64 v[144:145], v[144:145], 0, s[66:67]
	global_load_dwordx4 v[224:227], v[144:145], off
	global_load_dwordx4 v[228:231], v[144:145], off offset:64
	global_load_dwordx4 v[232:235], v[144:145], off offset:512
	global_load_dwordx4 v[236:239], v[144:145], off offset:576
	v_lshl_add_u64 v[144:145], v[144:145], 0, s[66:67]
	s_waitcnt vmcnt(4)
	v_pk_mul_f32 v[126:127], v[126:127], v[242:243]
	v_pk_mul_f32 v[124:125], v[124:125], v[240:241]
	v_pk_add_f32 v[126:127], v[126:127], v[210:211]
	v_pk_add_f32 v[124:125], v[124:125], v[208:209]
	v_pk_mul_f32 v[122:123], v[122:123], v[246:247]
	v_pk_mul_f32 v[120:121], v[120:121], v[244:245]
	v_pk_add_f32 v[122:123], v[122:123], v[214:215]
	v_pk_add_f32 v[120:121], v[120:121], v[212:213]
	v_pk_mul_f32 v[118:119], v[118:119], v[250:251]
	v_pk_mul_f32 v[116:117], v[116:117], v[248:249]
	v_pk_add_f32 v[118:119], v[118:119], v[218:219]
	v_pk_add_f32 v[116:117], v[116:117], v[216:217]
	v_pk_mul_f32 v[114:115], v[114:115], v[186:187]
	v_pk_mul_f32 v[112:113], v[112:113], v[184:185]
	v_pk_add_f32 v[114:115], v[114:115], v[222:223]
	v_pk_add_f32 v[112:113], v[112:113], v[220:221]
	v_pk_mul_f32 v[140:141], v[124:125], v[124:125]
	v_pk_fma_f32 v[140:141], v[126:127], v[126:127], v[140:141]
	v_add_f32_e32 v188, v188, v140
	v_add_f32_e32 v188, v188, v141
	v_pk_mul_f32 v[140:141], v[120:121], v[120:121]
	v_pk_fma_f32 v[140:141], v[122:123], v[122:123], v[140:141]
	v_add_f32_e32 v188, v188, v140
	v_add_f32_e32 v188, v188, v141
	v_pk_mul_f32 v[140:141], v[116:117], v[116:117]
	v_pk_fma_f32 v[140:141], v[118:119], v[118:119], v[140:141]
	v_add_f32_e32 v188, v188, v140
	v_add_f32_e32 v188, v188, v141
	v_pk_mul_f32 v[140:141], v[112:113], v[112:113]
	v_pk_fma_f32 v[140:141], v[114:115], v[114:115], v[140:141]
	v_add_f32_e32 v188, v188, v140
	v_add_f32_e32 v188, v188, v141
	global_load_dwordx4 v[208:211], v[144:145], off
	global_load_dwordx4 v[212:215], v[144:145], off offset:64
	global_load_dwordx4 v[216:219], v[144:145], off offset:512
	global_load_dwordx4 v[220:223], v[144:145], off offset:576
	v_lshl_add_u64 v[144:145], v[144:145], 0, s[66:67]
	s_waitcnt vmcnt(4)
	v_pk_mul_f32 v[110:111], v[110:111], v[242:243]
	v_pk_mul_f32 v[108:109], v[108:109], v[240:241]
	v_pk_add_f32 v[110:111], v[110:111], v[226:227]
	v_pk_add_f32 v[108:109], v[108:109], v[224:225]
	v_pk_mul_f32 v[106:107], v[106:107], v[246:247]
	v_pk_mul_f32 v[104:105], v[104:105], v[244:245]
	v_pk_add_f32 v[106:107], v[106:107], v[230:231]
	v_pk_add_f32 v[104:105], v[104:105], v[228:229]
	v_pk_mul_f32 v[102:103], v[102:103], v[250:251]
	v_pk_mul_f32 v[100:101], v[100:101], v[248:249]
	v_pk_add_f32 v[102:103], v[102:103], v[234:235]
	v_pk_add_f32 v[100:101], v[100:101], v[232:233]
	v_pk_mul_f32 v[98:99], v[98:99], v[186:187]
	v_pk_mul_f32 v[96:97], v[96:97], v[184:185]
	v_pk_add_f32 v[98:99], v[98:99], v[238:239]
	v_pk_add_f32 v[96:97], v[96:97], v[236:237]
	v_pk_mul_f32 v[140:141], v[108:109], v[108:109]
	v_pk_fma_f32 v[140:141], v[110:111], v[110:111], v[140:141]
	v_add_f32_e32 v189, v189, v140
	v_add_f32_e32 v189, v189, v141
	v_pk_mul_f32 v[140:141], v[104:105], v[104:105]
	v_pk_fma_f32 v[140:141], v[106:107], v[106:107], v[140:141]
	v_add_f32_e32 v189, v189, v140
	v_add_f32_e32 v189, v189, v141
	v_pk_mul_f32 v[140:141], v[100:101], v[100:101]
	v_pk_fma_f32 v[140:141], v[102:103], v[102:103], v[140:141]
	v_add_f32_e32 v189, v189, v140
	v_add_f32_e32 v189, v189, v141
	v_pk_mul_f32 v[140:141], v[96:97], v[96:97]
	v_pk_fma_f32 v[140:141], v[98:99], v[98:99], v[140:141]
	v_add_f32_e32 v189, v189, v140
	v_add_f32_e32 v189, v189, v141
	global_load_dwordx4 v[224:227], v[144:145], off
	global_load_dwordx4 v[228:231], v[144:145], off offset:64
	global_load_dwordx4 v[232:235], v[144:145], off offset:512
	global_load_dwordx4 v[236:239], v[144:145], off offset:576
	v_lshl_add_u64 v[144:145], v[144:145], 0, s[68:69]
	s_waitcnt vmcnt(4)
;     __device__ __forceinline__ void operator()(const Acc& acc, const Unit& u, int wr, int wc, int fr, int fq) const {
;     ...
;             for (int m = 0; m < 4; ++m) { const int row = u.pm * 256 + ai * 128 + wr * 64 + m * 16 + fr;
;                 const float* base = xp ? (row < MP ? xp + (size_t)row * D : xs + (size_t)(row - MP) * D) : X + (size_t)row * D;
;                 const float* gp = gate + (size_t)mod_row(row) * 6144;
; #pragma unroll
;                 for (int bj = 0; bj < 2; ++bj)
; #pragma unroll
;                     for (int n = 0; n < 2; ++n) { const int col = u.pn * 256 + bj * 128 + wc * 32 + n * 16 + fq * 4;
;                         const f32x4 ga = *(const f32x4*)(gp + col) * acc[ai][bj][m][n];
;                         if (u.split) { *(f32x4*)(part + ((size_t)(u.k0 >> 8) * MS + (row - MP)) * D + col) = ga;
;                         } else *(f32x4*)(X + (size_t)row * D + col) = *(const f32x4*)(base + col) + ga; } }
; template <bool FINAL>
; __device__ __forceinline__ void norm_rows(const float* xp, const float* xs, const float* X, const float* g, const float* sh, const float* sc, bf16_t* XN, float* out, int gw, int NGW, int lane, const float* part, int nsplit) {
;     ...
;         for (int j = 0; j < 4; ++j) s += (v[j][0] * v[j][0] + v[j][1] * v[j][1]) + (v[j][2] * v[j][2] + v[j][3] * v[j][3]);
	v_pk_mul_f32 v[94:95], v[94:95], v[242:243]
	v_pk_mul_f32 v[92:93], v[92:93], v[240:241]
	v_pk_add_f32 v[94:95], v[94:95], v[210:211]
	v_pk_add_f32 v[92:93], v[92:93], v[208:209]
	v_pk_mul_f32 v[90:91], v[90:91], v[246:247]
	v_pk_mul_f32 v[88:89], v[88:89], v[244:245]
	v_pk_add_f32 v[90:91], v[90:91], v[214:215]
	v_pk_add_f32 v[88:89], v[88:89], v[212:213]
	v_pk_mul_f32 v[86:87], v[86:87], v[250:251]
	v_pk_mul_f32 v[84:85], v[84:85], v[248:249]
	v_pk_add_f32 v[86:87], v[86:87], v[218:219]
	v_pk_add_f32 v[84:85], v[84:85], v[216:217]
	v_pk_mul_f32 v[82:83], v[82:83], v[186:187]
	v_pk_mul_f32 v[80:81], v[80:81], v[184:185]
	v_pk_add_f32 v[82:83], v[82:83], v[222:223]
	v_pk_add_f32 v[80:81], v[80:81], v[220:221]
	v_pk_mul_f32 v[140:141], v[92:93], v[92:93]
	v_pk_fma_f32 v[140:141], v[94:95], v[94:95], v[140:141]
	v_add_f32_e32 v190, v190, v140
	v_add_f32_e32 v190, v190, v141
	v_pk_mul_f32 v[140:141], v[88:89], v[88:89]
	v_pk_fma_f32 v[140:141], v[90:91], v[90:91], v[140:141]
	v_add_f32_e32 v190, v190, v140
	v_add_f32_e32 v190, v190, v141
	v_pk_mul_f32 v[140:141], v[84:85], v[84:85]
	v_pk_fma_f32 v[140:141], v[86:87], v[86:87], v[140:141]
	v_add_f32_e32 v190, v190, v140
	v_add_f32_e32 v190, v190, v141
	v_pk_mul_f32 v[140:141], v[80:81], v[80:81]
	v_pk_fma_f32 v[140:141], v[82:83], v[82:83], v[140:141]
	v_add_f32_e32 v190, v190, v140
	v_add_f32_e32 v190, v190, v141
	global_load_dwordx4 v[208:211], v[144:145], off
	global_load_dwordx4 v[212:215], v[144:145], off offset:64
	global_load_dwordx4 v[216:219], v[144:145], off offset:512
	global_load_dwordx4 v[220:223], v[144:145], off offset:576
	v_lshl_add_u64 v[144:145], v[144:145], 0, s[66:67]
	s_waitcnt vmcnt(4)
	v_pk_mul_f32 v[78:79], v[78:79], v[242:243]
	v_pk_mul_f32 v[76:77], v[76:77], v[240:241]
	v_pk_add_f32 v[78:79], v[78:79], v[226:227]
	v_pk_add_f32 v[76:77], v[76:77], v[224:225]
	v_pk_mul_f32 v[74:75], v[74:75], v[246:247]
	v_pk_mul_f32 v[72:73], v[72:73], v[244:245]
	v_pk_add_f32 v[74:75], v[74:75], v[230:231]
	v_pk_add_f32 v[72:73], v[72:73], v[228:229]
	v_pk_mul_f32 v[70:71], v[70:71], v[250:251]
	v_pk_mul_f32 v[68:69], v[68:69], v[248:249]
	v_pk_add_f32 v[70:71], v[70:71], v[234:235]
	v_pk_add_f32 v[68:69], v[68:69], v[232:233]
	v_pk_mul_f32 v[66:67], v[66:67], v[186:187]
	v_pk_mul_f32 v[64:65], v[64:65], v[184:185]
	v_pk_add_f32 v[66:67], v[66:67], v[238:239]
	v_pk_add_f32 v[64:65], v[64:65], v[236:237]
	v_pk_mul_f32 v[140:141], v[76:77], v[76:77]
	v_pk_fma_f32 v[140:141], v[78:79], v[78:79], v[140:141]
	v_add_f32_e32 v191, v191, v140
	v_add_f32_e32 v191, v191, v141
	v_pk_mul_f32 v[140:141], v[72:73], v[72:73]
	v_pk_fma_f32 v[140:141], v[74:75], v[74:75], v[140:141]
	v_add_f32_e32 v191, v191, v140
	v_add_f32_e32 v191, v191, v141
	v_pk_mul_f32 v[140:141], v[68:69], v[68:69]
	v_pk_fma_f32 v[140:141], v[70:71], v[70:71], v[140:141]
	v_add_f32_e32 v191, v191, v140
	v_add_f32_e32 v191, v191, v141
	v_pk_mul_f32 v[140:141], v[64:65], v[64:65]
	v_pk_fma_f32 v[140:141], v[66:67], v[66:67], v[140:141]
	v_add_f32_e32 v191, v191, v140
	v_add_f32_e32 v191, v191, v141
	global_load_dwordx4 v[224:227], v[144:145], off
	global_load_dwordx4 v[228:231], v[144:145], off offset:64
	global_load_dwordx4 v[232:235], v[144:145], off offset:512
	global_load_dwordx4 v[236:239], v[144:145], off offset:576
	v_lshl_add_u64 v[144:145], v[144:145], 0, s[66:67]
	s_waitcnt vmcnt(4)
	v_pk_mul_f32 v[62:63], v[62:63], v[242:243]
	v_pk_mul_f32 v[60:61], v[60:61], v[240:241]
	v_pk_add_f32 v[62:63], v[62:63], v[210:211]
	v_pk_add_f32 v[60:61], v[60:61], v[208:209]
	v_pk_mul_f32 v[58:59], v[58:59], v[246:247]
	v_pk_mul_f32 v[56:57], v[56:57], v[244:245]
	v_pk_add_f32 v[58:59], v[58:59], v[214:215]
	v_pk_add_f32 v[56:57], v[56:57], v[212:213]
	v_pk_mul_f32 v[54:55], v[54:55], v[250:251]
	v_pk_mul_f32 v[52:53], v[52:53], v[248:249]
	v_pk_add_f32 v[54:55], v[54:55], v[218:219]
	v_pk_add_f32 v[52:53], v[52:53], v[216:217]
	v_pk_mul_f32 v[50:51], v[50:51], v[186:187]
	v_pk_mul_f32 v[48:49], v[48:49], v[184:185]
	v_pk_add_f32 v[50:51], v[50:51], v[222:223]
	v_pk_add_f32 v[48:49], v[48:49], v[220:221]
	v_pk_mul_f32 v[140:141], v[60:61], v[60:61]
	v_pk_fma_f32 v[140:141], v[62:63], v[62:63], v[140:141]
	v_add_f32_e32 v192, v192, v140
	v_add_f32_e32 v192, v192, v141
	v_pk_mul_f32 v[140:141], v[56:57], v[56:57]
	v_pk_fma_f32 v[140:141], v[58:59], v[58:59], v[140:141]
	v_add_f32_e32 v192, v192, v140
	v_add_f32_e32 v192, v192, v141
	v_pk_mul_f32 v[140:141], v[52:53], v[52:53]
	v_pk_fma_f32 v[140:141], v[54:55], v[54:55], v[140:141]
	v_add_f32_e32 v192, v192, v140
	v_add_f32_e32 v192, v192, v141
	v_pk_mul_f32 v[140:141], v[48:49], v[48:49]
	v_pk_fma_f32 v[140:141], v[50:51], v[50:51], v[140:141]
	v_add_f32_e32 v192, v192, v140
	v_add_f32_e32 v192, v192, v141
	global_load_dwordx4 v[208:211], v[144:145], off
	global_load_dwordx4 v[212:215], v[144:145], off offset:64
	global_load_dwordx4 v[216:219], v[144:145], off offset:512
	global_load_dwordx4 v[220:223], v[144:145], off offset:576
	v_lshl_add_u64 v[144:145], v[144:145], 0, s[66:67]
	s_waitcnt vmcnt(4)
;     __device__ __forceinline__ void operator()(const Acc& acc, const Unit& u, int wr, int wc, int fr, int fq) const {
;     ...
;             for (int m = 0; m < 4; ++m) { const int row = u.pm * 256 + ai * 128 + wr * 64 + m * 16 + fr;
;                 const float* base = xp ? (row < MP ? xp + (size_t)row * D : xs + (size_t)(row - MP) * D) : X + (size_t)row * D;
;                 const float* gp = gate + (size_t)mod_row(row) * 6144;
; #pragma unroll
;                 for (int bj = 0; bj < 2; ++bj)
; #pragma unroll
;                     for (int n = 0; n < 2; ++n) { const int col = u.pn * 256 + bj * 128 + wc * 32 + n * 16 + fq * 4;
;                         const f32x4 ga = *(const f32x4*)(gp + col) * acc[ai][bj][m][n];
;                         if (u.split) { *(f32x4*)(part + ((size_t)(u.k0 >> 8) * MS + (row - MP)) * D + col) = ga;
;                         } else *(f32x4*)(X + (size_t)row * D + col) = *(const f32x4*)(base + col) + ga; } }
; template <bool FINAL>
; __device__ __forceinline__ void norm_rows(const float* xp, const float* xs, const float* X, const float* g, const float* sh, const float* sc, bf16_t* XN, float* out, int gw, int NGW, int lane, const float* part, int nsplit) {
;     ...
;         for (int j = 0; j < 4; ++j) s += (v[j][0] * v[j][0] + v[j][1] * v[j][1]) + (v[j][2] * v[j][2] + v[j][3] * v[j][3]);
;         const float rstd = 1.0f / sqrtf(wave_sum(s) * (1.0f / D) + EPS);
	v_pk_mul_f32 v[46:47], v[46:47], v[242:243]
	v_pk_mul_f32 v[44:45], v[44:45], v[240:241]
	v_pk_add_f32 v[46:47], v[46:47], v[226:227]
	v_pk_add_f32 v[44:45], v[44:45], v[224:225]
	v_pk_mul_f32 v[42:43], v[42:43], v[246:247]
	v_pk_mul_f32 v[40:41], v[40:41], v[244:245]
	v_pk_add_f32 v[42:43], v[42:43], v[230:231]
	v_pk_add_f32 v[40:41], v[40:41], v[228:229]
	v_pk_mul_f32 v[38:39], v[38:39], v[250:251]
	v_pk_mul_f32 v[36:37], v[36:37], v[248:249]
	v_pk_add_f32 v[38:39], v[38:39], v[234:235]
	v_pk_add_f32 v[36:37], v[36:37], v[232:233]
	v_pk_mul_f32 v[34:35], v[34:35], v[186:187]
	v_pk_mul_f32 v[32:33], v[32:33], v[184:185]
	v_pk_add_f32 v[34:35], v[34:35], v[238:239]
	v_pk_add_f32 v[32:33], v[32:33], v[236:237]
	v_pk_mul_f32 v[140:141], v[44:45], v[44:45]
	v_pk_fma_f32 v[140:141], v[46:47], v[46:47], v[140:141]
	v_add_f32_e32 v193, v193, v140
	v_add_f32_e32 v193, v193, v141
	v_pk_mul_f32 v[140:141], v[40:41], v[40:41]
	v_pk_fma_f32 v[140:141], v[42:43], v[42:43], v[140:141]
	v_add_f32_e32 v193, v193, v140
	v_add_f32_e32 v193, v193, v141
	v_pk_mul_f32 v[140:141], v[36:37], v[36:37]
	v_pk_fma_f32 v[140:141], v[38:39], v[38:39], v[140:141]
	v_add_f32_e32 v193, v193, v140
	v_add_f32_e32 v193, v193, v141
	v_pk_mul_f32 v[140:141], v[32:33], v[32:33]
	v_pk_fma_f32 v[140:141], v[34:35], v[34:35], v[140:141]
	v_add_f32_e32 v193, v193, v140
	v_add_f32_e32 v193, v193, v141
	global_load_dwordx4 v[224:227], v[144:145], off
	global_load_dwordx4 v[228:231], v[144:145], off offset:64
	global_load_dwordx4 v[232:235], v[144:145], off offset:512
	global_load_dwordx4 v[236:239], v[144:145], off offset:576
	s_waitcnt vmcnt(4)
	v_pk_mul_f32 v[30:31], v[30:31], v[242:243]
	v_pk_mul_f32 v[28:29], v[28:29], v[240:241]
	v_pk_add_f32 v[30:31], v[30:31], v[210:211]
	v_pk_add_f32 v[28:29], v[28:29], v[208:209]
	v_pk_mul_f32 v[26:27], v[26:27], v[246:247]
	v_pk_mul_f32 v[24:25], v[24:25], v[244:245]
	v_pk_add_f32 v[26:27], v[26:27], v[214:215]
	v_pk_add_f32 v[24:25], v[24:25], v[212:213]
	v_pk_mul_f32 v[22:23], v[22:23], v[250:251]
	v_pk_mul_f32 v[20:21], v[20:21], v[248:249]
	v_pk_add_f32 v[22:23], v[22:23], v[218:219]
	v_pk_add_f32 v[20:21], v[20:21], v[216:217]
	v_pk_mul_f32 v[18:19], v[18:19], v[186:187]
	v_pk_mul_f32 v[16:17], v[16:17], v[184:185]
	v_pk_add_f32 v[18:19], v[18:19], v[222:223]
	v_pk_add_f32 v[16:17], v[16:17], v[220:221]
	v_pk_mul_f32 v[140:141], v[28:29], v[28:29]
	v_pk_fma_f32 v[140:141], v[30:31], v[30:31], v[140:141]
	v_add_f32_e32 v194, v194, v140
	v_add_f32_e32 v194, v194, v141
	v_pk_mul_f32 v[140:141], v[24:25], v[24:25]
	v_pk_fma_f32 v[140:141], v[26:27], v[26:27], v[140:141]
	v_add_f32_e32 v194, v194, v140
	v_add_f32_e32 v194, v194, v141
	v_pk_mul_f32 v[140:141], v[20:21], v[20:21]
	v_pk_fma_f32 v[140:141], v[22:23], v[22:23], v[140:141]
	v_add_f32_e32 v194, v194, v140
	v_add_f32_e32 v194, v194, v141
	v_pk_mul_f32 v[140:141], v[16:17], v[16:17]
	v_pk_fma_f32 v[140:141], v[18:19], v[18:19], v[140:141]
	v_add_f32_e32 v194, v194, v140
	v_add_f32_e32 v194, v194, v141
	s_waitcnt vmcnt(0)
	v_pk_mul_f32 v[14:15], v[14:15], v[242:243]
	v_pk_mul_f32 v[12:13], v[12:13], v[240:241]
	v_pk_add_f32 v[14:15], v[14:15], v[226:227]
	v_pk_add_f32 v[12:13], v[12:13], v[224:225]
	v_pk_mul_f32 v[10:11], v[10:11], v[246:247]
	v_pk_mul_f32 v[8:9], v[8:9], v[244:245]
	v_pk_add_f32 v[10:11], v[10:11], v[230:231]
	v_pk_add_f32 v[8:9], v[8:9], v[228:229]
	v_pk_mul_f32 v[6:7], v[6:7], v[250:251]
	v_pk_mul_f32 v[4:5], v[4:5], v[248:249]
	v_pk_add_f32 v[6:7], v[6:7], v[234:235]
	v_pk_add_f32 v[4:5], v[4:5], v[232:233]
	v_pk_mul_f32 v[2:3], v[2:3], v[186:187]
	v_pk_mul_f32 v[0:1], v[0:1], v[184:185]
	v_pk_add_f32 v[2:3], v[2:3], v[238:239]
	v_pk_add_f32 v[0:1], v[0:1], v[236:237]
	v_pk_mul_f32 v[140:141], v[12:13], v[12:13]
	v_pk_fma_f32 v[140:141], v[14:15], v[14:15], v[140:141]
	v_add_f32_e32 v195, v195, v140
	v_add_f32_e32 v195, v195, v141
	v_pk_mul_f32 v[140:141], v[8:9], v[8:9]
	v_pk_fma_f32 v[140:141], v[10:11], v[10:11], v[140:141]
	v_add_f32_e32 v195, v195, v140
	v_add_f32_e32 v195, v195, v141
	v_pk_mul_f32 v[140:141], v[4:5], v[4:5]
	v_pk_fma_f32 v[140:141], v[6:7], v[6:7], v[140:141]
	v_add_f32_e32 v195, v195, v140
	v_add_f32_e32 v195, v195, v141
	v_pk_mul_f32 v[140:141], v[0:1], v[0:1]
	v_pk_fma_f32 v[140:141], v[2:3], v[2:3], v[140:141]
	v_add_f32_e32 v195, v195, v140
	v_add_f32_e32 v195, v195, v141
	ds_swizzle_b32 v208, v188 offset:swizzle(SWAP,16)
	ds_swizzle_b32 v209, v189 offset:swizzle(SWAP,16)
	ds_swizzle_b32 v210, v190 offset:swizzle(SWAP,16)
	ds_swizzle_b32 v211, v191 offset:swizzle(SWAP,16)
	ds_swizzle_b32 v212, v192 offset:swizzle(SWAP,16)
	ds_swizzle_b32 v213, v193 offset:swizzle(SWAP,16)
	ds_swizzle_b32 v214, v194 offset:swizzle(SWAP,16)
	ds_swizzle_b32 v215, v195 offset:swizzle(SWAP,16)
	s_waitcnt lgkmcnt(0)
	v_add_f32_e32 v188, v188, v208
	v_add_f32_e32 v189, v189, v209
	v_add_f32_e32 v190, v190, v210
	v_add_f32_e32 v191, v191, v211
	v_add_f32_e32 v192, v192, v212
	v_add_f32_e32 v193, v193, v213
	v_add_f32_e32 v194, v194, v214
	v_add_f32_e32 v195, v195, v215
	v_mov_b32_e32 v208, v188
	v_mov_b32_e32 v209, v189
	v_mov_b32_e32 v210, v190
	v_mov_b32_e32 v211, v191
	v_mov_b32_e32 v212, v192
	v_mov_b32_e32 v213, v193
	v_mov_b32_e32 v214, v194
	v_mov_b32_e32 v215, v195
	s_nop 1
	v_permlane32_swap_b32 v188, v208
	v_permlane32_swap_b32 v189, v209
	v_permlane32_swap_b32 v190, v210
	v_permlane32_swap_b32 v191, v211
	v_permlane32_swap_b32 v192, v212
	v_permlane32_swap_b32 v193, v213
	v_permlane32_swap_b32 v194, v214
	v_permlane32_swap_b32 v195, v215
	s_nop 1
	v_add_f32_e32 v188, v188, v208
	v_add_f32_e32 v189, v189, v209
	v_add_f32_e32 v190, v190, v210
	v_add_f32_e32 v191, v191, v211
	v_add_f32_e32 v192, v192, v212
	v_add_f32_e32 v193, v193, v213
	v_add_f32_e32 v194, v194, v214
	v_add_f32_e32 v195, v195, v215
	v_readlane_b32 s25, v253, 2
	s_nop 3
	s_and_b32 s27, s25, 3
	s_lshl_b32 s27, s27, 10
	s_add_i32 s27, s27, 0x20800
	v_lshl_add_u32 v143, v142, 2, s27
	ds_write_b32 v143, v188
	ds_write_b32 v143, v189 offset:64
	ds_write_b32 v143, v190 offset:128
	ds_write_b32 v143, v191 offset:192
	ds_write_b32 v143, v192 offset:512
	ds_write_b32 v143, v193 offset:576
	ds_write_b32 v143, v194 offset:640
	ds_write_b32 v143, v195 offset:704
	v_mbcnt_lo_u32_b32 v207, -1, 0
	v_mbcnt_hi_u32_b32 v207, -1, v207
	s_lshl_b32 s27, s25, 6
	v_add_u32_e32 v207, s27, v207
	v_lshlrev_b32_e32 v207, 2, v207
	s_sub_u32 s70, s10, 0x7800000
	s_subb_u32 s71, s11, 0
	s_lshl_b32 s74, s55, 11
	s_add_u32 s70, s70, s74
	s_addc_u32 s71, s71, 0
	s_lshl_b32 s32, s96, 3
	s_add_i32 s32, s32, 8
	s_or_b32 s32, s32, 0xc0de0000
	s_waitcnt lgkmcnt(0)
	s_barrier
; template <bool FINAL>
; __device__ __forceinline__ void norm_rows(const float* xp, const float* xs, const float* X, const float* g, const float* sh, const float* sc, bf16_t* XN, float* out, int gw, int NGW, int lane, const float* part, int nsplit) {
;     ...
;         const float rstd = 1.0f / sqrtf(wave_sum(s) * (1.0f / D) + EPS);
;         const int mr = mod_row(row);
;         if (!FINAL && xp && row >= MP) {
; #pragma unroll
;             for (int j = 0; j < 4; ++j) *(f32x4*)((float*)X + (size_t)row * D + 4 * lane + 256 * j) = v[j]; }
; #pragma unroll
;         for (int j = 0; j < 4; ++j) { const int col = 4 * lane + 256 * j; const f32x4 gg = *(const f32x4*)(g + col);
;             if (FINAL) { *(f32x4*)(out + (size_t)row * D + col) = v[j] * rstd * gg; }
	s_cmp_lt_u32 s25, 4
	s_cbranch_scc0 .Lfz_dnf_nopub
	v_add_u32_e32 v140, 0x20800, v207
	ds_read_b32 v212, v140
	ds_read_b32 v213, v140 offset:1024
	ds_read_b32 v214, v140 offset:2048
	ds_read_b32 v215, v140 offset:3072
	v_lshlrev_b32_e32 v188, 1, v207
	s_lshl_b32 s74, s53, 17
	v_add_u32_e32 v141, s74, v188
	s_waitcnt lgkmcnt(0)
	v_add_f32_e32 v212, v212, v213
	v_add_f32_e32 v212, v212, v214
	v_add_f32_e32 v212, v212, v215
	v_mov_b32_e32 v213, s32
	global_store_dwordx2 v141, v[212:213], s[70:71] sc0 sc1
.Lfz_dnf_nopub:
	v_mov_b32_e32 v140, 0x20508
	ds_read_b64 v[140:141], v140
	s_waitcnt lgkmcnt(0)
	v_readfirstlane_b32 s2, v140
	v_readfirstlane_b32 s3, v141
	s_nop 4
	global_load_dwordx4 v[208:211], v159, s[2:3]
	global_load_dwordx4 v[212:215], v159, s[2:3] offset:64
	global_load_dwordx4 v[216:219], v159, s[2:3] offset:512
	global_load_dwordx4 v[220:223], v159, s[2:3] offset:576
	s_cmp_lt_u32 s25, 4
	s_cbranch_scc0 .Lfz_dnf_norstd
	v_add_u32_e32 v189, 0x20000, v188
	v_add_u32_e32 v190, 0x40000, v188
	v_add_u32_e32 v191, 0x60000, v188
	s_mov_b32 s65, 0

; template <bool FINAL>
; __device__ __forceinline__ void norm_rows(const float* xp, const float* xs, const float* X, const float* g, const float* sh, const float* sc, bf16_t* XN, float* out, int gw, int NGW, int lane, const float* part, int nsplit) {
;     ...
;         for (int j = 0; j < 4; ++j) { const int col = 4 * lane + 256 * j; const f32x4 gg = *(const f32x4*)(g + col);
;             if (FINAL) { *(f32x4*)(out + (size_t)row * D + col) = v[j] * rstd * gg; }
.Lfz_dnf_norstd:
	s_waitcnt lgkmcnt(0)
	s_barrier
	v_lshlrev_b32_e32 v145, 2, v142
	v_add_u32_e32 v145, 0x21800, v145
	ds_read_b32 v188, v145
	ds_read_b32 v189, v145 offset:64
	ds_read_b32 v190, v145 offset:128
	ds_read_b32 v191, v145 offset:192
	ds_read_b32 v192, v145 offset:512
	ds_read_b32 v193, v145 offset:576
	ds_read_b32 v194, v145 offset:640
	ds_read_b32 v195, v145 offset:704
	s_waitcnt vmcnt(0) lgkmcnt(0)
	v_mul_f32_e32 v124, v124, v188
	v_mul_f32_e32 v125, v125, v188
	v_mul_f32_e32 v126, v126, v188
	v_mul_f32_e32 v127, v127, v188
	v_pk_mul_f32 v[124:125], v[208:209], v[124:125]
	v_pk_mul_f32 v[126:127], v[210:211], v[126:127]
	global_store_dwordx4 v[146:147], v[124:127], off
	v_mul_f32_e32 v120, v120, v188
	v_mul_f32_e32 v121, v121, v188
	v_mul_f32_e32 v122, v122, v188
	v_mul_f32_e32 v123, v123, v188
	v_pk_mul_f32 v[120:121], v[212:213], v[120:121]
	v_pk_mul_f32 v[122:123], v[214:215], v[122:123]
	global_store_dwordx4 v[146:147], v[120:123], off offset:64
	v_mul_f32_e32 v116, v116, v188
	v_mul_f32_e32 v117, v117, v188
	v_mul_f32_e32 v118, v118, v188
	v_mul_f32_e32 v119, v119, v188
	v_pk_mul_f32 v[116:117], v[216:217], v[116:117]
	v_pk_mul_f32 v[118:119], v[218:219], v[118:119]
	global_store_dwordx4 v[146:147], v[116:119], off offset:512
	v_mul_f32_e32 v112, v112, v188
	v_mul_f32_e32 v113, v113, v188
	v_mul_f32_e32 v114, v114, v188
	v_mul_f32_e32 v115, v115, v188
	v_pk_mul_f32 v[112:113], v[220:221], v[112:113]
	v_pk_mul_f32 v[114:115], v[222:223], v[114:115]
	global_store_dwordx4 v[146:147], v[112:115], off offset:576
	v_lshl_add_u64 v[146:147], v[146:147], 0, s[66:67]
	v_mul_f32_e32 v108, v108, v189
	v_mul_f32_e32 v109, v109, v189
	v_mul_f32_e32 v110, v110, v189
	v_mul_f32_e32 v111, v111, v189
	v_pk_mul_f32 v[108:109], v[208:209], v[108:109]
	v_pk_mul_f32 v[110:111], v[210:211], v[110:111]
	global_store_dwordx4 v[146:147], v[108:111], off
	v_mul_f32_e32 v104, v104, v189
	v_mul_f32_e32 v105, v105, v189
	v_mul_f32_e32 v106, v106, v189
	v_mul_f32_e32 v107, v107, v189
	v_pk_mul_f32 v[104:105], v[212:213], v[104:105]
	v_pk_mul_f32 v[106:107], v[214:215], v[106:107]
	global_store_dwordx4 v[146:147], v[104:107], off offset:64
	v_mul_f32_e32 v100, v100, v189
	v_mul_f32_e32 v101, v101, v189
	v_mul_f32_e32 v102, v102, v189
	v_mul_f32_e32 v103, v103, v189
	v_pk_mul_f32 v[100:101], v[216:217], v[100:101]
	v_pk_mul_f32 v[102:103], v[218:219], v[102:103]
	global_store_dwordx4 v[146:147], v[100:103], off offset:512
	v_mul_f32_e32 v96, v96, v189
	v_mul_f32_e32 v97, v97, v189
	v_mul_f32_e32 v98, v98, v189
	v_mul_f32_e32 v99, v99, v189
	v_pk_mul_f32 v[96:97], v[220:221], v[96:97]
	v_pk_mul_f32 v[98:99], v[222:223], v[98:99]
	global_store_dwordx4 v[146:147], v[96:99], off offset:576
	v_lshl_add_u64 v[146:147], v[146:147], 0, s[66:67]
	v_mul_f32_e32 v92, v92, v190
	v_mul_f32_e32 v93, v93, v190
	v_mul_f32_e32 v94, v94, v190
	v_mul_f32_e32 v95, v95, v190
	v_pk_mul_f32 v[92:93], v[208:209], v[92:93]
	v_pk_mul_f32 v[94:95], v[210:211], v[94:95]
	global_store_dwordx4 v[146:147], v[92:95], off
	v_mul_f32_e32 v88, v88, v190
	v_mul_f32_e32 v89, v89, v190
	v_mul_f32_e32 v90, v90, v190
	v_mul_f32_e32 v91, v91, v190
	v_pk_mul_f32 v[88:89], v[212:213], v[88:89]
	v_pk_mul_f32 v[90:91], v[214:215], v[90:91]
	global_store_dwordx4 v[146:147], v[88:91], off offset:64
	v_mul_f32_e32 v84, v84, v190
	v_mul_f32_e32 v85, v85, v190
	v_mul_f32_e32 v86, v86, v190
	v_mul_f32_e32 v87, v87, v190
	v_pk_mul_f32 v[84:85], v[216:217], v[84:85]
	v_pk_mul_f32 v[86:87], v[218:219], v[86:87]
	global_store_dwordx4 v[146:147], v[84:87], off offset:512
	v_mul_f32_e32 v80, v80, v190
	v_mul_f32_e32 v81, v81, v190
	v_mul_f32_e32 v82, v82, v190
	v_mul_f32_e32 v83, v83, v190
	v_pk_mul_f32 v[80:81], v[220:221], v[80:81]
	v_pk_mul_f32 v[82:83], v[222:223], v[82:83]
	global_store_dwordx4 v[146:147], v[80:83], off offset:576
	v_lshl_add_u64 v[146:147], v[146:147], 0, s[66:67]
	v_mul_f32_e32 v76, v76, v191
	v_mul_f32_e32 v77, v77, v191
	v_mul_f32_e32 v78, v78, v191
	v_mul_f32_e32 v79, v79, v191
	v_pk_mul_f32 v[76:77], v[208:209], v[76:77]
	v_pk_mul_f32 v[78:79], v[210:211], v[78:79]
	global_store_dwordx4 v[146:147], v[76:79], off
	v_mul_f32_e32 v72, v72, v191
	v_mul_f32_e32 v73, v73, v191
	v_mul_f32_e32 v74, v74, v191
	v_mul_f32_e32 v75, v75, v191
	v_pk_mul_f32 v[72:73], v[212:213], v[72:73]
	v_pk_mul_f32 v[74:75], v[214:215], v[74:75]
	global_store_dwordx4 v[146:147], v[72:75], off offset:64
	v_mul_f32_e32 v68, v68, v191
	v_mul_f32_e32 v69, v69, v191
	v_mul_f32_e32 v70, v70, v191
	v_mul_f32_e32 v71, v71, v191
	v_pk_mul_f32 v[68:69], v[216:217], v[68:69]
	v_pk_mul_f32 v[70:71], v[218:219], v[70:71]
	global_store_dwordx4 v[146:147], v[68:71], off offset:512
; template <bool FINAL>
; __device__ __forceinline__ void norm_rows(const float* xp, const float* xs, const float* X, const float* g, const float* sh, const float* sc, bf16_t* XN, float* out, int gw, int NGW, int lane, const float* part, int nsplit) {
;     ...
;         for (int j = 0; j < 4; ++j) { const int col = 4 * lane + 256 * j; const f32x4 gg = *(const f32x4*)(g + col);
;             if (FINAL) { *(f32x4*)(out + (size_t)row * D + col) = v[j] * rstd * gg; }
	v_mul_f32_e32 v64, v64, v191
	v_mul_f32_e32 v65, v65, v191
	v_mul_f32_e32 v66, v66, v191
	v_mul_f32_e32 v67, v67, v191
	v_pk_mul_f32 v[64:65], v[220:221], v[64:65]
	v_pk_mul_f32 v[66:67], v[222:223], v[66:67]
	global_store_dwordx4 v[146:147], v[64:67], off offset:576
	v_lshl_add_u64 v[146:147], v[146:147], 0, s[68:69]
	v_mul_f32_e32 v60, v60, v192
	v_mul_f32_e32 v61, v61, v192
	v_mul_f32_e32 v62, v62, v192
	v_mul_f32_e32 v63, v63, v192
	v_pk_mul_f32 v[60:61], v[208:209], v[60:61]
	v_pk_mul_f32 v[62:63], v[210:211], v[62:63]
	global_store_dwordx4 v[146:147], v[60:63], off
	v_mul_f32_e32 v56, v56, v192
	v_mul_f32_e32 v57, v57, v192
	v_mul_f32_e32 v58, v58, v192
	v_mul_f32_e32 v59, v59, v192
	v_pk_mul_f32 v[56:57], v[212:213], v[56:57]
	v_pk_mul_f32 v[58:59], v[214:215], v[58:59]
	global_store_dwordx4 v[146:147], v[56:59], off offset:64
	v_mul_f32_e32 v52, v52, v192
	v_mul_f32_e32 v53, v53, v192
	v_mul_f32_e32 v54, v54, v192
	v_mul_f32_e32 v55, v55, v192
	v_pk_mul_f32 v[52:53], v[216:217], v[52:53]
	v_pk_mul_f32 v[54:55], v[218:219], v[54:55]
	global_store_dwordx4 v[146:147], v[52:55], off offset:512
	v_mul_f32_e32 v48, v48, v192
	v_mul_f32_e32 v49, v49, v192
	v_mul_f32_e32 v50, v50, v192
	v_mul_f32_e32 v51, v51, v192
	v_pk_mul_f32 v[48:49], v[220:221], v[48:49]
	v_pk_mul_f32 v[50:51], v[222:223], v[50:51]
	global_store_dwordx4 v[146:147], v[48:51], off offset:576
	v_lshl_add_u64 v[146:147], v[146:147], 0, s[66:67]
	v_mul_f32_e32 v44, v44, v193
	v_mul_f32_e32 v45, v45, v193
	v_mul_f32_e32 v46, v46, v193
	v_mul_f32_e32 v47, v47, v193
	v_pk_mul_f32 v[44:45], v[208:209], v[44:45]
	v_pk_mul_f32 v[46:47], v[210:211], v[46:47]
	global_store_dwordx4 v[146:147], v[44:47], off
	v_mul_f32_e32 v40, v40, v193
	v_mul_f32_e32 v41, v41, v193
	v_mul_f32_e32 v42, v42, v193
	v_mul_f32_e32 v43, v43, v193
	v_pk_mul_f32 v[40:41], v[212:213], v[40:41]
	v_pk_mul_f32 v[42:43], v[214:215], v[42:43]
	global_store_dwordx4 v[146:147], v[40:43], off offset:64
	v_mul_f32_e32 v36, v36, v193
	v_mul_f32_e32 v37, v37, v193
	v_mul_f32_e32 v38, v38, v193
	v_mul_f32_e32 v39, v39, v193
	v_pk_mul_f32 v[36:37], v[216:217], v[36:37]
	v_pk_mul_f32 v[38:39], v[218:219], v[38:39]
	global_store_dwordx4 v[146:147], v[36:39], off offset:512
	v_mul_f32_e32 v32, v32, v193
	v_mul_f32_e32 v33, v33, v193
	v_mul_f32_e32 v34, v34, v193
	v_mul_f32_e32 v35, v35, v193
	v_pk_mul_f32 v[32:33], v[220:221], v[32:33]
	v_pk_mul_f32 v[34:35], v[222:223], v[34:35]
	global_store_dwordx4 v[146:147], v[32:35], off offset:576
	v_lshl_add_u64 v[146:147], v[146:147], 0, s[66:67]
	v_mul_f32_e32 v28, v28, v194
	v_mul_f32_e32 v29, v29, v194
	v_mul_f32_e32 v30, v30, v194
	v_mul_f32_e32 v31, v31, v194
	v_pk_mul_f32 v[28:29], v[208:209], v[28:29]
	v_pk_mul_f32 v[30:31], v[210:211], v[30:31]
	global_store_dwordx4 v[146:147], v[28:31], off
	v_mul_f32_e32 v24, v24, v194
	v_mul_f32_e32 v25, v25, v194
	v_mul_f32_e32 v26, v26, v194
	v_mul_f32_e32 v27, v27, v194
	v_pk_mul_f32 v[24:25], v[212:213], v[24:25]
	v_pk_mul_f32 v[26:27], v[214:215], v[26:27]
	global_store_dwordx4 v[146:147], v[24:27], off offset:64
	v_mul_f32_e32 v20, v20, v194
	v_mul_f32_e32 v21, v21, v194
	v_mul_f32_e32 v22, v22, v194
	v_mul_f32_e32 v23, v23, v194
	v_pk_mul_f32 v[20:21], v[216:217], v[20:21]
	v_pk_mul_f32 v[22:23], v[218:219], v[22:23]
	global_store_dwordx4 v[146:147], v[20:23], off offset:512
	v_mul_f32_e32 v16, v16, v194
	v_mul_f32_e32 v17, v17, v194
	v_mul_f32_e32 v18, v18, v194
	v_mul_f32_e32 v19, v19, v194
	v_pk_mul_f32 v[16:17], v[220:221], v[16:17]
	v_pk_mul_f32 v[18:19], v[222:223], v[18:19]
	global_store_dwordx4 v[146:147], v[16:19], off offset:576
	v_lshl_add_u64 v[146:147], v[146:147], 0, s[66:67]
	v_mul_f32_e32 v12, v12, v195
	v_mul_f32_e32 v13, v13, v195
	v_mul_f32_e32 v14, v14, v195
	v_mul_f32_e32 v15, v15, v195
	v_pk_mul_f32 v[12:13], v[208:209], v[12:13]
	v_pk_mul_f32 v[14:15], v[210:211], v[14:15]
	global_store_dwordx4 v[146:147], v[12:15], off
	v_mul_f32_e32 v8, v8, v195
	v_mul_f32_e32 v9, v9, v195
	v_mul_f32_e32 v10, v10, v195
	v_mul_f32_e32 v11, v11, v195
	v_pk_mul_f32 v[8:9], v[212:213], v[8:9]
	v_pk_mul_f32 v[10:11], v[214:215], v[10:11]
	global_store_dwordx4 v[146:147], v[8:11], off offset:64
	v_mul_f32_e32 v4, v4, v195
	v_mul_f32_e32 v5, v5, v195
	v_mul_f32_e32 v6, v6, v195
	v_mul_f32_e32 v7, v7, v195
	v_pk_mul_f32 v[4:5], v[216:217], v[4:5]
	v_pk_mul_f32 v[6:7], v[218:219], v[6:7]
	global_store_dwordx4 v[146:147], v[4:7], off offset:512
	v_mul_f32_e32 v0, v0, v195
	v_mul_f32_e32 v1, v1, v195
	v_mul_f32_e32 v2, v2, v195
	v_mul_f32_e32 v3, v3, v195
	v_pk_mul_f32 v[0:1], v[220:221], v[0:1]
	v_pk_mul_f32 v[2:3], v[222:223], v[2:3]
	global_store_dwordx4 v[146:147], v[0:3], off offset:576
	s_branch .Lepi_dn_done
